# P2: attention mask/dist hoisted to VGPRs + packed score fma, V/K prologue loads overlapped, ret_u V loads hoisted
# baseline (speedup 1.0000x reference)
; DEV int tidx() { int t = threadIdx.x; asm volatile("" : "+v"(t)); return t; }
; DEV bf16_t f2bf(float f) { return (bf16_t)(cvt_pk_bf16(f, 0.f) & 0xffffu); }
; DEV float bflo(unsigned w) { return __uint_as_float(w << 16); }
; DEV float bfhi(unsigned w) { return __uint_as_float(w & 0xffff0000u); }
; DEV float log_gamma(int h) { return log1pf(-exp2f(-5.0f - (float)h)); }
; DEV void ret_u_item(const Params& p, int item, unsigned char* smem) {
;   const int bh = item >> 5, n = item & 31, b = bh >> 2, h = bh & 3;
;   const bf16_t* Z = (const bf16_t*)(p.ws + WS_Z);
;   float* U = (float*)(p.ws + WS_H);
;   bf16_t* Kt = (bf16_t*)smem;
;   bf16_t* Vt = (bf16_t*)(smem + 64 * 272);
;   const int tid = tidx(), lane = tid & 63, w = tid >> 6, fr = lane & 15, fq = lane >> 4;
;   const size_t rowbase = (size_t)b * SEQ + n * 128;
;   const float lg = log_gamma(h);
; #pragma unroll
;   for (int i = 0; i < 2; ++i) {
;     const int c = tid + i * 512, r = c & 127, kc = c >> 7;
;     const u32x4 v = *(const u32x4*)(Z + (rowbase + r) * NIN + RK + h * 64 + kc * 8);
;     const float sc = 0.125f * __expf(lg * (float)(127 - r));
;     bf16_t* dst = Kt + (kc * 8) * 136 + r;
;     dst[0 * 136] = f2bf(bflo(v.x) * sc); dst[1 * 136] = f2bf(bfhi(v.x) * sc);
;     dst[2 * 136] = f2bf(bflo(v.y) * sc); dst[3 * 136] = f2bf(bfhi(v.y) * sc);
;     dst[4 * 136] = f2bf(bflo(v.z) * sc); dst[5 * 136] = f2bf(bfhi(v.z) * sc);
;     dst[6 * 136] = f2bf(bflo(v.w) * sc); dst[7 * 136] = f2bf(bfhi(v.w) * sc);
;   }
; #pragma unroll
;   for (int i = 0; i < 4; ++i) {
;     const int c = tid + i * 512, r = c & 127, kc = c >> 7;
;     const u32x4 v = *(const u32x4*)(Z + (rowbase + r) * NIN + RV + h * 128 + kc * 8);
;     bf16_t* dst = Vt + (kc * 8) * 136 + r;
;     dst[0 * 136] = (bf16_t)(v.x & 0xffff); dst[1 * 136] = (bf16_t)(v.x >> 16);
;     dst[2 * 136] = (bf16_t)(v.y & 0xffff); dst[3 * 136] = (bf16_t)(v.y >> 16);
;     dst[4 * 136] = (bf16_t)(v.z & 0xffff); dst[5 * 136] = (bf16_t)(v.z >> 16);
;     dst[6 * 136] = (bf16_t)(v.w & 0xffff); dst[7 * 136] = (bf16_t)(v.w >> 16);
;   }
.LBB0_429:
	s_cmpk_gt_i32 s93, 0xff
	s_mov_b64 s[0:1], -1
	s_cbranch_scc0 .LBB0_431
	s_bfe_u32 s1, s93, 0x20005
	v_cvt_f32_ubyte0_e32 v0, s1
	v_sub_f32_e32 v0, 0xc0a00000, v0
	s_mov_b32 s4, 0xc2fc0000
	v_cmp_gt_f32_e32 vcc, s4, v0
	s_add_i32 s0, s93, 0xffffff00
	s_lshl_b32 s2, s0, 5
	s_waitcnt lgkmcnt(0)
	v_cndmask_b32_e32 v1, 0, v203, vcc
	s_lshl_b32 s3, s0, 7
	v_add_f32_e32 v0, v0, v1
	s_and_b32 s2, s2, 0x3000
	s_and_b32 s3, s3, 0xf80
	v_exp_f32_e32 v0, v0
	s_or_b32 s4, s2, s3
	s_and_b64 s[2:3], vcc, exec
	s_cselect_b32 s2, 0xffffffc0, 0
	v_ldexp_f32 v16, v0, s2
	v_sub_f32_e32 v2, 1.0, v16
	v_add_f32_e32 v0, -1.0, v2
	v_sub_f32_e32 v1, v0, v2
	v_add_f32_e32 v1, 1.0, v1
	v_sub_f32_e64 v0, -v16, v0
	v_add_f32_e32 v3, v0, v1
	v_frexp_mant_f32_e32 v4, v2
	v_cvt_f64_f32_e32 v[0:1], v2
	s_mov_b32 s2, 0x3f2aaaab
	v_frexp_exp_i32_f64_e32 v0, v[0:1]
	v_cmp_gt_f32_e32 vcc, s2, v4
	v_mov_b32_e32 v27, v171
	s_lshl_b32 s6, s1, 7
	v_subbrev_co_u32_e32 v6, vcc, 0, v0, vcc
	v_sub_u32_e32 v0, 0, v6
	v_ldexp_f32 v1, v2, v0
	v_add_f32_e32 v2, -1.0, v1
	v_add_f32_e32 v5, 1.0, v1
	v_ldexp_f32 v0, v3, v0
	v_add_f32_e32 v3, 1.0, v2
	v_add_f32_e32 v7, -1.0, v5
	v_sub_f32_e32 v3, v1, v3
	v_sub_f32_e32 v1, v1, v7
	v_add_f32_e32 v3, v0, v3
	v_add_f32_e32 v0, v0, v1
	v_add_f32_e32 v1, v5, v0
	v_rcp_f32_e32 v7, v1
	v_add_f32_e32 v4, v2, v3
	v_sub_f32_e32 v2, v4, v2
	v_sub_f32_e32 v2, v3, v2
	v_sub_f32_e32 v3, v1, v5
	v_mul_f32_e32 v14, v4, v7
	v_sub_f32_e32 v0, v0, v3
	v_mul_f32_e32 v3, v1, v14
	v_fma_f32 v5, v14, v1, -v3
	v_fmac_f32_e32 v5, v14, v0
	v_add_f32_e32 v8, v3, v5
	v_sub_f32_e32 v9, v4, v8
	v_sub_f32_e32 v4, v4, v9
	v_sub_f32_e32 v3, v8, v3
	v_sub_f32_e32 v4, v4, v8
	v_add_f32_e32 v2, v2, v4
	v_sub_f32_e32 v3, v3, v5
	v_add_f32_e32 v2, v3, v2
	v_add_f32_e32 v15, v9, v2
	v_mul_f32_e32 v17, v7, v15
	v_mul_f32_e32 v3, v1, v17
	v_fma_f32 v18, v17, v1, -v3
	v_fmac_f32_e32 v18, v17, v0
	v_sub_f32_e32 v0, v9, v15
	v_and_b32_e32 v22, 0x7f, v27
	v_add_f32_e32 v19, v2, v0
	v_or_b32_e32 v0, s4, v22
	v_mul_u32_u24_e32 v168, 0x3600, v0
	v_ashrrev_i32_e32 v0, 4, v27
	v_and_b32_e32 v10, -8, v0
	v_lshl_add_u64 v[8:9], s[30:31], 0, v[168:169]
	v_ashrrev_i32_e32 v11, 31, v10
	v_lshl_add_u64 v[4:5], v[8:9], 0, s[6:7]
	v_lshlrev_b64 v[12:13], 1, v[10:11]
	v_add_f32_e32 v20, v3, v18
	v_lshl_add_u64 v[0:1], v[4:5], 0, v[12:13]
	v_sub_f32_e32 v21, v20, v3
	global_load_dwordx4 v[0:3], v[0:1], off offset:512
	v_sub_f32_e32 v11, v15, v20
	v_sub_f32_e32 v15, v15, v11
	v_sub_f32_e32 v15, v15, v20
	v_add_f32_e32 v15, v19, v15
	v_sub_f32_e32 v18, v21, v18
	v_add_f32_e32 v15, v18, v15
	v_add_f32_e32 v11, v11, v15
	v_cvt_f32_i32_e32 v6, v6
	v_mul_f32_e32 v7, v7, v11
	v_add_f32_e32 v11, v14, v17
	v_sub_f32_e32 v14, v11, v14
	v_sub_f32_e32 v14, v17, v14
	v_add_f32_e32 v7, v14, v7
	v_mul_f32_e32 v18, 0x3f317218, v6
	s_mov_b32 s2, 0x3f317218
	v_add_f32_e32 v14, v11, v7
	v_fma_f32 v19, v6, s2, -v18
	v_mul_f32_e32 v15, v14, v14
	v_fmac_f32_e32 v19, 0xb102e308, v6
	v_sub_f32_e32 v6, v14, v11
	v_fmamk_f32 v17, v15, 0x3e9b6dac, v201
	v_sub_f32_e32 v6, v7, v6
	v_add_f32_e32 v7, v18, v19
	v_fmaak_f32 v17, v15, v17, 0x3f2aaada
	v_sub_f32_e32 v11, v7, v18
	v_ldexp_f32 v18, v14, 1
	v_mul_f32_e32 v14, v14, v15
	v_mul_f32_e32 v14, v14, v17
	v_add_f32_e32 v15, v18, v14
	v_sub_f32_e32 v17, v15, v18
	v_ldexp_f32 v6, v6, 1
	v_sub_f32_e32 v14, v14, v17
	v_add_f32_e32 v6, v6, v14
	v_add_f32_e32 v14, v15, v6
	v_sub_f32_e32 v15, v14, v15
	v_add_f32_e32 v18, v7, v14
	v_sub_f32_e32 v17, v6, v15
	v_sub_f32_e32 v6, v18, v7
	v_sub_f32_e32 v15, v18, v6
	v_sub_f32_e32 v11, v19, v11
	v_sub_f32_e32 v7, v7, v15
	v_sub_f32_e32 v6, v14, v6
	v_add_f32_e32 v19, v6, v7
	v_add_f32_e32 v20, v11, v17
	v_add_u32_e32 v6, 0x200, v27
	v_sub_f32_e32 v21, v20, v11
	v_ashrrev_i32_e32 v6, 4, v6
	v_sub_f32_e32 v23, v20, v21
	v_and_b32_e32 v24, -8, v6
	v_ashrrev_i32_e32 v25, 31, v24
	v_sub_f32_e32 v11, v11, v23
	v_sub_f32_e32 v17, v17, v21
	v_lshlrev_b64 v[14:15], 1, v[24:25]
	v_add_f32_e32 v11, v17, v11
	v_add_f32_e32 v17, v20, v19
	v_lshl_add_u64 v[4:5], v[4:5], 0, v[14:15]
	v_add_f32_e32 v19, v18, v17
	global_load_dwordx4 v[4:7], v[4:5], off offset:512
	v_sub_f32_e32 v18, v19, v18
	v_sub_f32_e32 v17, v17, v18
	v_add_f32_e32 v11, v11, v17
	v_add_f32_e32 v11, v19, v11
	v_cmp_nlt_f32_e32 vcc, 1.0, v16
	s_mov_b32 s2, 0x33800000
	v_lshl_add_u32 v26, v22, 1, 0
	v_cndmask_b32_e32 v11, v204, v11, vcc
	v_cmp_neq_f32_e32 vcc, 1.0, v16
	s_movk_i32 s4, 0x110
	s_lshl_b32 s6, s1, 8
	v_cndmask_b32_e32 v11, v205, v11, vcc
	v_cmp_gt_f32_e32 vcc, s2, v16
	s_movk_i32 s2, 0x7f
	v_lshl_add_u64 v[20:21], v[8:9], 0, s[6:7]
	v_lshl_add_u64 v[186:187], v[20:21], 0, v[12:13]
	global_load_dwordx4 v[218:221], v[186:187], off offset:1024
	v_add_u32_e32 v188, 0x400, v27
	v_ashrrev_i32_e32 v188, 4, v188
	v_and_b32_e32 v188, -8, v188
	v_ashrrev_i32_e32 v189, 31, v188
	v_lshl_add_u64 v[190:191], v[188:189], 1, v[20:21]
	global_load_dwordx4 v[222:225], v[190:191], off offset:1024
	v_add_u32_e32 v192, 0x600, v27
	v_ashrrev_i32_e32 v192, 4, v192
	v_and_b32_e32 v192, -8, v192
	v_ashrrev_i32_e32 v193, 31, v192
	v_lshl_add_u64 v[190:191], v[192:193], 1, v[20:21]
	global_load_dwordx4 v[226:229], v[190:191], off offset:1024
	v_lshl_add_u64 v[186:187], v[20:21], 0, v[14:15]
	global_load_dwordx4 v[230:233], v[186:187], off offset:1024
	v_cndmask_b32_e64 v11, v11, -v16, vcc
	v_bitop3_b32 v16, v27, s2, v27 bitop3:0xc
	v_cvt_f32_ubyte0_e32 v16, v16
	v_mul_f32_e32 v11, v11, v16
	v_mul_f32_e32 v11, 0x3fb8aa3b, v11
	v_exp_f32_e32 v11, v11
	s_waitcnt vmcnt(4)
; DEV bf16_t f2bf(float f) { return (bf16_t)(cvt_pk_bf16(f, 0.f) & 0xffffu); }
; DEV float bflo(unsigned w) { return __uint_as_float(w << 16); }
; DEV float bfhi(unsigned w) { return __uint_as_float(w & 0xffff0000u); }
; DEV f32x4 mfma16(bf16x4 a, bf16x4 b, f32x4 c) { return __builtin_amdgcn_mfma_f32_16x16x16bf16_1k(a, b, c, 0, 0, 0); }
; DEV void ret_u_item(const Params& p, int item, unsigned char* smem) {
;     ...
; #pragma unroll
;   for (int i = 0; i < 2; ++i) {
;     const int c = tid + i * 512, r = c & 127, kc = c >> 7;
;     const u32x4 v = *(const u32x4*)(Z + (rowbase + r) * NIN + RK + h * 64 + kc * 8);
;     const float sc = 0.125f * __expf(lg * (float)(127 - r));
;     bf16_t* dst = Kt + (kc * 8) * 136 + r;
;     dst[0 * 136] = f2bf(bflo(v.x) * sc); dst[1 * 136] = f2bf(bfhi(v.x) * sc);
;     dst[2 * 136] = f2bf(bflo(v.y) * sc); dst[3 * 136] = f2bf(bfhi(v.y) * sc);
;     dst[4 * 136] = f2bf(bflo(v.z) * sc); dst[5 * 136] = f2bf(bfhi(v.z) * sc);
;     dst[6 * 136] = f2bf(bflo(v.w) * sc); dst[7 * 136] = f2bf(bfhi(v.w) * sc);
;   }
; #pragma unroll
;   for (int i = 0; i < 4; ++i) {
;     const int c = tid + i * 512, r = c & 127, kc = c >> 7;
;     const u32x4 v = *(const u32x4*)(Z + (rowbase + r) * NIN + RV + h * 128 + kc * 8);
;     bf16_t* dst = Vt + (kc * 8) * 136 + r;
;     dst[0 * 136] = (bf16_t)(v.x & 0xffff); dst[1 * 136] = (bf16_t)(v.x >> 16);
;     dst[2 * 136] = (bf16_t)(v.y & 0xffff); dst[3 * 136] = (bf16_t)(v.y >> 16);
;     dst[4 * 136] = (bf16_t)(v.z & 0xffff); dst[5 * 136] = (bf16_t)(v.z >> 16);
;     dst[6 * 136] = (bf16_t)(v.w & 0xffff); dst[7 * 136] = (bf16_t)(v.w >> 16);
;   }
;   __syncthreads();
;   f32x4 acc[4];
; #pragma unroll
;   for (int dt = 0; dt < 4; ++dt) acc[dt] = (f32x4){0.f, 0.f, 0.f, 0.f};
; #pragma unroll
;   for (int jt = 0; jt < 8; ++jt) {
;     const bf16x4 vf = *(const bf16x4*)(Vt + (w * 16 + fr) * 136 + jt * 16 + fq * 4);
; #pragma unroll
;     for (int dt = 0; dt < 4; ++dt) {
;       const bf16x4 kf = *(const bf16x4*)(Kt + (dt * 16 + fr) * 136 + jt * 16 + fq * 4);
;       acc[dt] = mfma16(vf, kf, acc[dt]);
;     }
;   }
	v_lshlrev_b32_e32 v16, 16, v0
	v_and_b32_e32 v0, 0xffff0000, v0
	v_mad_u64_u32 v[28:29], s[2:3], v10, s4, v[26:27]
	v_mul_f32_e32 v25, 0x3e000000, v11
	v_mul_f32_e32 v0, v25, v0
	v_cvt_pk_bf16_f32 v0, v0, s0
	ds_write_b16 v28, v0 offset:272
	v_lshlrev_b32_e32 v0, 16, v1
	v_mul_f32_e32 v0, v25, v0
	v_cvt_pk_bf16_f32 v0, v0, s0
	ds_write_b16 v28, v0 offset:544
	v_and_b32_e32 v0, 0xffff0000, v1
	v_mul_f32_e32 v0, v25, v0
	v_lshl_add_u64 v[8:9], v[20:21], 0, v[12:13]
	v_mul_f32_e32 v12, v25, v16
	v_add_u32_e32 v16, 0x400, v27
	v_cvt_pk_bf16_f32 v29, v0, s0
	v_add_u32_e32 v0, 0x600, v27
	v_ashrrev_i32_e32 v16, 4, v16
	v_ashrrev_i32_e32 v0, 4, v0
	v_and_b32_e32 v30, -8, v16
	v_and_b32_e32 v0, -8, v0
	v_cvt_pk_bf16_f32 v12, v12, s0
	v_ashrrev_i32_e32 v31, 31, v30
	v_ashrrev_i32_e32 v1, 31, v0
	ds_write_b16 v28, v12
	v_lshl_add_u64 v[12:13], v[20:21], 0, v[14:15]
	v_lshl_add_u64 v[16:17], v[30:31], 1, v[20:21]
	v_lshl_add_u64 v[20:21], v[0:1], 1, v[20:21]
	v_lshlrev_b32_e32 v1, 16, v2
	v_mul_f32_e32 v1, v25, v1
	v_cvt_pk_bf16_f32 v1, v1, s0
	ds_write_b16 v28, v1 offset:1088
	v_and_b32_e32 v1, 0xffff0000, v2
	v_mul_f32_e32 v1, v25, v1
	v_cvt_pk_bf16_f32 v1, v1, s0
	ds_write_b16 v28, v1 offset:1360
	v_lshlrev_b32_e32 v1, 16, v3
	v_mul_f32_e32 v1, v25, v1
	v_cvt_pk_bf16_f32 v1, v1, s0
	ds_write_b16 v28, v1 offset:1632
	v_and_b32_e32 v1, 0xffff0000, v3
	v_mul_f32_e32 v1, v25, v1
	v_cvt_pk_bf16_f32 v1, v1, s0
	ds_write_b16 v28, v1 offset:1904
	v_mad_u64_u32 v[2:3], s[2:3], v24, s4, v[26:27]
	ds_write_b16 v28, v29 offset:816
	v_ashrrev_i32_e32 v36, 2, v27
	v_and_b32_e32 v39, 15, v27
	s_lshl_b32 s6, s0, 13
	v_lshlrev_b32_e32 v1, 16, v4
	v_mul_f32_e32 v1, v25, v1
	v_cvt_pk_bf16_f32 v1, v1, s0
	ds_write_b16 v2, v1
	v_and_b32_e32 v1, 0xffff0000, v4
	v_mul_f32_e32 v1, v25, v1
	v_cvt_pk_bf16_f32 v1, v1, s0
	ds_write_b16 v2, v1 offset:272
	v_lshlrev_b32_e32 v1, 16, v5
	v_mul_f32_e32 v1, v25, v1
	v_cvt_pk_bf16_f32 v1, v1, s0
	ds_write_b16 v2, v1 offset:544
	v_and_b32_e32 v1, 0xffff0000, v5
	v_mul_f32_e32 v1, v25, v1
	v_cvt_pk_bf16_f32 v1, v1, s0
	ds_write_b16 v2, v1 offset:816
	v_lshlrev_b32_e32 v1, 16, v6
	v_mul_f32_e32 v1, v25, v1
	v_cvt_pk_bf16_f32 v1, v1, s0
	ds_write_b16 v2, v1 offset:1088
	v_and_b32_e32 v1, 0xffff0000, v6
	v_mul_f32_e32 v1, v25, v1
	v_cvt_pk_bf16_f32 v1, v1, s0
	ds_write_b16 v2, v1 offset:1360
	v_lshlrev_b32_e32 v1, 16, v7
	v_mul_f32_e32 v1, v25, v1
	v_cvt_pk_bf16_f32 v1, v1, s0
	ds_write_b16 v2, v1 offset:1632
	v_and_b32_e32 v1, 0xffff0000, v7
	v_mul_f32_e32 v1, v25, v1
	v_cvt_pk_bf16_f32 v1, v1, s0
	ds_write_b16 v2, v1 offset:1904
	s_waitcnt vmcnt(3)
	ds_write_b16 v28, v218 offset:17408
	ds_write_b16_d16_hi v28, v218 offset:17680
	ds_write_b16 v28, v219 offset:17952
	ds_write_b16_d16_hi v28, v219 offset:18224
	ds_write_b16 v28, v220 offset:18496
	ds_write_b16_d16_hi v28, v220 offset:18768
	ds_write_b16 v28, v221 offset:19040
	ds_write_b16_d16_hi v28, v221 offset:19312
	s_waitcnt vmcnt(0)
	ds_write_b16 v2, v230 offset:17408
	ds_write_b16_d16_hi v2, v230 offset:17680
	ds_write_b16 v2, v231 offset:17952
	ds_write_b16_d16_hi v2, v231 offset:18224
	ds_write_b16 v2, v232 offset:18496
	ds_write_b16_d16_hi v2, v232 offset:18768
	ds_write_b16 v2, v233 offset:19040
	ds_write_b16_d16_hi v2, v233 offset:19312
	v_mad_u64_u32 v[0:1], s[2:3], v0, s4, v[26:27]
	v_lshrrev_b32_e32 v1, 2, v27
	v_mad_u64_u32 v[2:3], s[2:3], v30, s4, v[26:27]
	v_and_b32_e32 v37, 12, v1
	ds_write_b16 v2, v222 offset:17408
	ds_write_b16_d16_hi v2, v222 offset:17680
	ds_write_b16 v2, v223 offset:17952
	ds_write_b16_d16_hi v2, v223 offset:18224
	ds_write_b16 v2, v224 offset:18496
	ds_write_b16_d16_hi v2, v224 offset:18768
	ds_write_b16 v2, v225 offset:19040
	ds_write_b16_d16_hi v2, v225 offset:19312
	ds_write_b16 v0, v226 offset:17408
	ds_write_b16_d16_hi v0, v226 offset:17680
	ds_write_b16 v0, v227 offset:17952
	ds_write_b16_d16_hi v0, v227 offset:18224
	ds_write_b16 v0, v228 offset:18496
	ds_write_b16_d16_hi v0, v228 offset:18768
	ds_write_b16 v0, v229 offset:19040
	ds_write_b16_d16_hi v0, v229 offset:19312
	v_bfi_b32 v0, -16, v36, v27
	v_lshl_add_u32 v4, v37, 1, 0
	v_mad_u64_u32 v[0:1], s[2:3], v0, s4, v[4:5]
	v_add_u32_e32 v38, 0x4000, v0
	s_waitcnt lgkmcnt(0)
	s_barrier
	ds_read2_b64 v[0:3], v38 offset0:128 offset1:132
	v_mad_u32_u24 v40, v39, s4, v4
	v_add_u32_e32 v41, 0x1000, v40
	ds_read2_b64 v[4:7], v40 offset1:4
	ds_read2_b64 v[12:15], v41 offset0:32 offset1:36
	v_add_u32_e32 v42, 0x2000, v40
	ds_read2_b64 v[20:23], v42 offset0:64 offset1:68
	s_waitcnt lgkmcnt(2)
	v_mfma_f32_16x16x16_bf16 v[8:11], v[0:1], v[4:5], 0
	v_add_u32_e32 v43, 0x3000, v40
	ds_read2_b64 v[28:31], v43 offset0:96 offset1:100
	s_lshl_b64 s[0:1], s[6:7], 2
	s_waitcnt lgkmcnt(2)
	v_mfma_f32_16x16x16_bf16 v[16:19], v[0:1], v[12:13], 0
	s_add_u32 s0, s24, s0
	s_addc_u32 s1, s25, s1
	s_waitcnt lgkmcnt(1)
	v_mfma_f32_16x16x16_bf16 v[24:27], v[0:1], v[20:21], 0
	v_mfma_f32_16x16x16_bf16 v[4:7], v[2:3], v[6:7], v[8:11]
	v_mfma_f32_16x16x16_bf16 v[8:11], v[2:3], v[14:15], v[16:19]
	s_nop 2
	ds_read2_b64 v[16:19], v38 offset0:136 offset1:140
	s_waitcnt lgkmcnt(1)
	v_mfma_f32_16x16x16_bf16 v[32:35], v[0:1], v[28:29], 0
	v_mfma_f32_16x16x16_bf16 v[12:15], v[2:3], v[22:23], v[24:27]
	ds_read2_b64 v[20:23], v40 offset0:8 offset1:12
	v_mfma_f32_16x16x16_bf16 v[0:3], v[2:3], v[30:31], v[32:35]
	s_nop 0
	ds_read2_b64 v[24:27], v41 offset0:40 offset1:44
	ds_read2_b64 v[28:31], v42 offset0:72 offset1:76
	s_nop 1
	ds_read2_b64 v[32:35], v43 offset0:104 offset1:108
	s_waitcnt lgkmcnt(3)
	v_mfma_f32_16x16x16_bf16 v[4:7], v[16:17], v[20:21], v[4:7]
	s_waitcnt lgkmcnt(2)
	v_mfma_f32_16x16x16_bf16 v[8:11], v[16:17], v[24:25], v[8:11]
	s_waitcnt lgkmcnt(1)
; DEV f32x4 mfma16(bf16x4 a, bf16x4 b, f32x4 c) { return __builtin_amdgcn_mfma_f32_16x16x16bf16_1k(a, b, c, 0, 0, 0); }
; DEV void attn_prompt_group(const Params& p, int l, int item, unsigned char* smem) {
;     ...
;     u32x4 v[4];
; #pragma unroll
;     for (int i = 0; i < 4; ++i) {
;       const int c = tid + i * 512, r = c & 255, kc = c >> 8;
;       const int tok = nb * 128 - 128 + r;
;       v[i] = (u32x4){0u, 0u, 0u, 0u};
;       if (tok >= 0) v[i] = *(const u32x4*)(Z + ((size_t)b * SEQ + tok) * NIN + AV + kvh * 64 + kc * 8);
;     }
; DEV void ret_u_item(const Params& p, int item, unsigned char* smem) {
;     ...
;   f32x4 acc[4];
; #pragma unroll
;   for (int dt = 0; dt < 4; ++dt) acc[dt] = (f32x4){0.f, 0.f, 0.f, 0.f};
; #pragma unroll
;   for (int jt = 0; jt < 8; ++jt) {
;     const bf16x4 vf = *(const bf16x4*)(Vt + (w * 16 + fr) * 136 + jt * 16 + fq * 4);
; #pragma unroll
;     for (int dt = 0; dt < 4; ++dt) {
;       const bf16x4 kf = *(const bf16x4*)(Kt + (dt * 16 + fr) * 136 + jt * 16 + fq * 4);
;       acc[dt] = mfma16(vf, kf, acc[dt]);
;     }
;   }
;   float* Uo = U + (size_t)(bh * 32 + n) * 8192;
; #pragma unroll
;   for (int dt = 0; dt < 4; ++dt)
; #pragma unroll
;     for (int jj = 0; jj < 4; ++jj) Uo[(w * 16 + fq * 4 + jj) * 64 + dt * 16 + fr] = acc[dt][jj];
;   __syncthreads();
	v_mfma_f32_16x16x16_bf16 v[12:15], v[16:17], v[28:29], v[12:15]
	s_waitcnt lgkmcnt(0)
	v_mfma_f32_16x16x16_bf16 v[0:3], v[16:17], v[32:33], v[0:3]
	v_mfma_f32_16x16x16_bf16 v[4:7], v[18:19], v[22:23], v[4:7]
	ds_read2_b64 v[20:23], v38 offset0:144 offset1:148
	v_mfma_f32_16x16x16_bf16 v[8:11], v[18:19], v[26:27], v[8:11]
	ds_read2_b64 v[24:27], v41 offset0:48 offset1:52
	v_mfma_f32_16x16x16_bf16 v[12:15], v[18:19], v[30:31], v[12:15]
	ds_read2_b64 v[28:31], v42 offset0:80 offset1:84
	v_mfma_f32_16x16x16_bf16 v[0:3], v[18:19], v[34:35], v[0:3]
	ds_read2_b64 v[16:19], v40 offset0:16 offset1:20
	ds_read2_b64 v[32:35], v43 offset0:112 offset1:116
	s_waitcnt lgkmcnt(1)
	v_mfma_f32_16x16x16_bf16 v[4:7], v[20:21], v[16:17], v[4:7]
	v_mfma_f32_16x16x16_bf16 v[8:11], v[20:21], v[24:25], v[8:11]
	v_mfma_f32_16x16x16_bf16 v[12:15], v[20:21], v[28:29], v[12:15]
	s_waitcnt lgkmcnt(0)
	v_mfma_f32_16x16x16_bf16 v[0:3], v[20:21], v[32:33], v[0:3]
	v_mfma_f32_16x16x16_bf16 v[4:7], v[22:23], v[18:19], v[4:7]
	ds_read2_b64 v[16:19], v38 offset0:152 offset1:156
	v_mfma_f32_16x16x16_bf16 v[8:11], v[22:23], v[26:27], v[8:11]
	ds_read2_b64 v[24:27], v41 offset0:56 offset1:60
	v_mfma_f32_16x16x16_bf16 v[12:15], v[22:23], v[30:31], v[12:15]
	ds_read2_b64 v[28:31], v42 offset0:88 offset1:92
	v_mfma_f32_16x16x16_bf16 v[0:3], v[22:23], v[34:35], v[0:3]
	ds_read2_b64 v[20:23], v40 offset0:24 offset1:28
	ds_read2_b64 v[32:35], v43 offset0:120 offset1:124
	s_waitcnt lgkmcnt(1)
	v_mfma_f32_16x16x16_bf16 v[4:7], v[16:17], v[20:21], v[4:7]
	v_mfma_f32_16x16x16_bf16 v[8:11], v[16:17], v[24:25], v[8:11]
	v_mfma_f32_16x16x16_bf16 v[12:15], v[16:17], v[28:29], v[12:15]
	s_waitcnt lgkmcnt(0)
	v_mfma_f32_16x16x16_bf16 v[0:3], v[16:17], v[32:33], v[0:3]
	v_and_or_b32 v16, v36, -16, v37
	v_lshlrev_b32_e32 v16, 6, v16
	v_or_b32_e32 v20, v39, v16
	v_mfma_f32_16x16x16_bf16 v[4:7], v[18:19], v[22:23], v[4:7]
	v_ashrrev_i32_e32 v17, 31, v16
	v_ashrrev_i32_e32 v21, 31, v20
	v_or_b32_e32 v16, 16, v20
	v_mfma_f32_16x16x16_bf16 v[8:11], v[18:19], v[26:27], v[8:11]
	v_mfma_f32_16x16x16_bf16 v[12:15], v[18:19], v[30:31], v[12:15]
	v_mfma_f32_16x16x16_bf16 v[0:3], v[18:19], v[34:35], v[0:3]
	v_lshl_add_u64 v[18:19], v[20:21], 2, s[0:1]
	v_mov_b32_e32 v21, v17
	global_store_dword v[18:19], v4, off
	v_lshl_add_u64 v[18:19], v[20:21], 2, s[0:1]
	global_store_dword v[18:19], v5, off offset:256
	global_store_dword v[18:19], v6, off offset:512
	global_store_dword v[18:19], v7, off offset:768
	global_store_dword v[18:19], v8, off offset:64
	v_lshl_add_u64 v[4:5], v[16:17], 2, s[0:1]
	v_or_b32_e32 v16, 32, v20
	global_store_dword v[4:5], v9, off offset:256
	global_store_dword v[4:5], v10, off offset:512
	global_store_dword v[4:5], v11, off offset:768
	global_store_dword v[18:19], v12, off offset:128
	v_lshl_add_u64 v[4:5], v[16:17], 2, s[0:1]
	v_or_b32_e32 v16, 48, v20
	global_store_dword v[4:5], v13, off offset:256
	global_store_dword v[4:5], v14, off offset:512
	global_store_dword v[4:5], v15, off offset:768
	global_store_dword v[18:19], v0, off offset:192
	v_lshl_add_u64 v[4:5], v[16:17], 2, s[0:1]
	global_store_dword v[4:5], v1, off offset:256
	global_store_dword v[4:5], v2, off offset:512
	global_store_dword v[4:5], v3, off offset:768
	s_barrier
	s_mov_b64 s[0:1], 0
.LBB0_431:
	s_andn2_b64 vcc, exec, s[0:1]
	s_cbranch_vccnz .LBB0_428
	s_ashr_i32 s0, s93, 6
	s_bfe_u32 s8, s93, 0x50001
	s_ashr_i32 s1, s0, 31
	v_mov_b32_e32 v74, v171
	s_lshl_b64 s[2:3], s[0:1], 12
	s_lshl_b32 s1, s8, 7
	s_addk_i32 s1, 0xff80
	v_and_b32_e32 v20, 0xff, v74
	v_add_u32_e32 v168, s1, v20
	s_waitcnt lgkmcnt(0)
	v_lshl_add_u64 v[0:1], s[2:3], 0, v[168:169]
	v_mov_b64_e32 v[2:3], s[30:31]
	s_and_b32 s9, s93, 1
	v_mad_u64_u32 v[2:3], s[4:5], v0, s95, v[2:3]
	v_mad_i32_i24 v3, v1, s95, v3
	s_lshl_b32 s6, s9, 7
	v_lshl_add_u64 v[0:1], v[2:3], 0, s[6:7]
	s_mov_b64 s[4:5], 0x1100
	v_cmp_lt_i32_e32 vcc, -1, v168
	v_lshl_add_u64 v[16:17], v[0:1], 0, s[4:5]
	v_ashrrev_i32_e32 v21, 5, v74
	v_add_u32_e32 v1, 0x200, v74
	v_ashrrev_i32_e32 v22, 5, v1
	v_add_u32_e32 v9, 0x400, v74
	v_ashrrev_i32_e32 v23, 5, v9
	v_add_u32_e32 v9, 0x600, v74
	v_ashrrev_i32_e32 v9, 5, v9
	v_and_b32_e32 v18, -8, v9
	v_mov_b64_e32 v[218:219], 0
	v_mov_b64_e32 v[220:221], 0
	v_mov_b64_e32 v[222:223], 0
	v_mov_b64_e32 v[224:225], 0
	v_mov_b64_e32 v[226:227], 0
	v_mov_b64_e32 v[228:229], 0
	v_mov_b64_e32 v[230:231], 0
	v_mov_b64_e32 v[232:233], 0
	s_and_saveexec_b64 s[4:5], vcc
	s_cbranch_execz .Lattn_vskip
	v_and_b32_e32 v2, -8, v21
	v_ashrrev_i32_e32 v3, 31, v2
	v_lshl_add_u64 v[2:3], v[2:3], 1, v[16:17]
	global_load_dwordx4 v[218:221], v[2:3], off
	v_and_b32_e32 v0, -8, v22
	v_ashrrev_i32_e32 v1, 31, v0
	v_lshl_add_u64 v[0:1], v[0:1], 1, v[16:17]
	global_load_dwordx4 v[222:225], v[0:1], off
	v_and_b32_e32 v10, -8, v23
	v_ashrrev_i32_e32 v11, 31, v10
	v_lshl_add_u64 v[10:11], v[10:11], 1, v[16:17]
	global_load_dwordx4 v[226:229], v[10:11], off
	v_ashrrev_i32_e32 v19, 31, v18
	v_lshl_add_u64 v[8:9], v[18:19], 1, v[16:17]
	global_load_dwordx4 v[230:233], v[8:9], off
.Lattn_vskip:
	s_or_b64 exec, exec, s[4:5]
	s_lshl_b32 s6, s9, 6
	v_lshl_add_u32 v16, v20, 1, 0
	v_and_b32_e32 v17, 0xffffff8, v21
	s_movk_i32 s9, 0x210
	v_mad_u64_u32 v[186:187], s[4:5], v17, s9, v[16:17]
	v_and_b32_e32 v4, 0xffffff8, v22
	v_mad_u64_u32 v[188:189], s[4:5], v4, s9, v[16:17]
	v_and_b32_e32 v0, 0xffffff8, v23
	v_mad_u64_u32 v[190:191], s[4:5], v0, s9, v[16:17]
	v_mad_u64_u32 v[192:193], s[4:5], v18, s9, v[16:17]
	v_ashrrev_i32_e32 v77, 6, v74
	v_lshlrev_b32_e32 v75, 4, v77
	v_and_b32_e32 v76, 15, v74
	v_add_u32_e32 v0, s1, v75
	v_or_b32_e32 v168, v0, v76
	v_cmp_lt_i32_e32 vcc, -1, v0
	v_lshl_add_u64 v[0:1], s[2:3], 0, v[168:169]
	v_mov_b64_e32 v[2:3], s[30:31]
	v_mad_u64_u32 v[2:3], s[4:5], v0, s95, v[2:3]
	v_mad_i32_i24 v3, v1, s95, v3
	s_lshl_b32 s6, s6, 1
	v_lshl_add_u64 v[0:1], v[2:3], 0, s[6:7]
	v_and_b32_e32 v168, 48, v74
	v_lshl_add_u64 v[0:1], v[0:1], 0, v[168:169]
	s_mov_b64 s[4:5], 0x1000
	v_lshl_add_u64 v[8:9], v[0:1], 0, s[4:5]
	v_mov_b32_e32 v0, 0
	v_mov_b32_e32 v4, 0
	v_mov_b32_e32 v5, 0
	v_mov_b32_e32 v6, 0
	v_mov_b32_e32 v7, 0
	s_and_saveexec_b64 s[4:5], vcc
	s_cbranch_execz .LBB0_442
	global_load_dwordx4 v[4:7], v[8:9], off

; DEV void attn_prompt_group(const Params& p, int l, int item, unsigned char* smem) {
;     ...
;   bf16x8 kf[9][2];
; #pragma unroll
;   for (int t = 0; t < 9; ++t) {
;     const int tok = nb * 128 - 128 + (w + t) * 16 + fr;
; #pragma unroll
;     for (int ks = 0; ks < 2; ++ks) {
;       u32x4 v = (u32x4){0u, 0u, 0u, 0u};
;       if (tok >= 0) v = *(const u32x4*)(Z + ((size_t)b * SEQ + tok) * NIN + AK + kvh * 64 + ks * 32 + fq * 8);
;       kf[t][ks] = __builtin_bit_cast(bf16x8, v);
;     }
;   }
;   __syncthreads();
.LBB0_476:
	s_or_b64 exec, exec, s[2:3]
	s_cmp_eq_u32 s8, 0
	s_cbranch_scc1 .Lattn_vw0
	s_waitcnt vmcnt(18)
	s_branch .Lattn_vw1

; DEV void attn_prompt_group(const Params& p, int l, int item, unsigned char* smem) {
;     ...
;     for (int i = 0; i < 4; ++i) {
;       const int c = tid + i * 512, r = c & 255, kc = c >> 8;
;       bf16_t* dst = Vt + (kc * 8) * 264 + r;
;       dst[0 * 264] = (bf16_t)(v[i].x & 0xffff); dst[1 * 264] = (bf16_t)(v[i].x >> 16);
;       dst[2 * 264] = (bf16_t)(v[i].y & 0xffff); dst[3 * 264] = (bf16_t)(v[i].y >> 16);
;       dst[4 * 264] = (bf16_t)(v[i].z & 0xffff); dst[5 * 264] = (bf16_t)(v[i].z >> 16);
;       dst[6 * 264] = (bf16_t)(v[i].w & 0xffff); dst[7 * 264] = (bf16_t)(v[i].w >> 16);
;     }
;     ...
;     for (int t = 0; t < 9; ++t)
; #pragma unroll
;       for (int j = 0; j < 4; ++j) {
;         const int si = (w + t) * 16 + fq * 4 + j;
;         const bool ok = (si > qi) && (si <= 128 + qi) && (nb > 0 || si >= 128);
;         const float sc = ok ? s[t][j] * 0.125f - slope * (float)(128 + qi - si) : -INFINITY;
.Lattn_vw1:
	ds_write_b16 v186, v218
	ds_write_b16_d16_hi v186, v218 offset:528
	ds_write_b16 v186, v219 offset:1056
	ds_write_b16_d16_hi v186, v219 offset:1584
	ds_write_b16 v186, v220 offset:2112
	ds_write_b16_d16_hi v186, v220 offset:2640
	ds_write_b16 v186, v221 offset:3168
	ds_write_b16_d16_hi v186, v221 offset:3696
	ds_write_b16 v188, v222
	ds_write_b16_d16_hi v188, v222 offset:528
	ds_write_b16 v188, v223 offset:1056
	ds_write_b16_d16_hi v188, v223 offset:1584
	ds_write_b16 v188, v224 offset:2112
	ds_write_b16_d16_hi v188, v224 offset:2640
	ds_write_b16 v188, v225 offset:3168
	ds_write_b16_d16_hi v188, v225 offset:3696
	ds_write_b16 v190, v226
	ds_write_b16_d16_hi v190, v226 offset:528
	ds_write_b16 v190, v227 offset:1056
	ds_write_b16_d16_hi v190, v227 offset:1584
	ds_write_b16 v190, v228 offset:2112
	ds_write_b16_d16_hi v190, v228 offset:2640
	ds_write_b16 v190, v229 offset:3168
	ds_write_b16_d16_hi v190, v229 offset:3696
	ds_write_b16 v192, v230
	ds_write_b16_d16_hi v192, v230 offset:528
	ds_write_b16 v192, v231 offset:1056
	ds_write_b16_d16_hi v192, v231 offset:1584
	ds_write_b16 v192, v232 offset:2112
	ds_write_b16_d16_hi v192, v232 offset:2640
	ds_write_b16 v192, v233 offset:3168
	ds_write_b16_d16_hi v192, v233 offset:3696
	v_cndmask_b32_e64 v72, 0, 1, s[34:35]
	v_readlane_b32 s2, v248, 46
	v_readfirstlane_b32 s1, v72
	s_lshl_b32 s1, s1, 2
	s_add_i32 s2, s2, s1
	s_ashr_i32 s3, s2, 31
	s_lshl_b64 s[2:3], s[2:3], 2
	s_add_u32 s18, s82, s2
	s_addc_u32 s19, s83, s3
	s_or_b32 s6, s1, 1
	v_lshlrev_b32_e32 v107, 2, v78
	s_cmp_lg_u32 s8, 0
	v_or_b32_e32 v108, v107, v75
	s_movk_i32 s1, 0x7f
	s_cselect_b64 s[88:89], -1, 0
	v_cmp_lt_i32_e32 vcc, s1, v108
	s_movk_i32 s84, 0x7e
	s_or_b64 s[36:37], s[88:89], vcc
	v_cmp_lt_i32_e32 vcc, s84, v108
	v_or_b32_e32 v110, 2, v108
	s_or_b64 s[38:39], s[88:89], vcc
	v_cmp_lt_i32_e32 vcc, s1, v110
	v_or_b32_e32 v111, 3, v108
	s_or_b64 s[40:41], s[88:89], vcc
	v_cmp_lt_i32_e32 vcc, s1, v111
	v_or_b32_e32 v112, v81, v107
	s_or_b64 s[60:61], s[88:89], vcc
	v_cmp_lt_i32_e32 vcc, s1, v112
	s_or_b64 s[62:63], s[88:89], vcc
	v_cmp_lt_i32_e32 vcc, s84, v112
	v_or_b32_e32 v114, 2, v112
	s_or_b64 s[64:65], s[88:89], vcc
	v_cmp_lt_i32_e32 vcc, s1, v114
	v_or_b32_e32 v115, 3, v112
	s_or_b64 s[66:67], s[88:89], vcc
	v_cmp_lt_i32_e32 vcc, s1, v115
	v_or_b32_e32 v116, v83, v107
	s_or_b64 s[68:69], s[88:89], vcc
	v_cmp_lt_i32_e32 vcc, s1, v116
	s_or_b64 s[70:71], s[88:89], vcc
	v_cmp_lt_i32_e32 vcc, s84, v116
	v_or_b32_e32 v118, 2, v116
	s_or_b64 s[72:73], s[88:89], vcc
	v_cmp_lt_i32_e32 vcc, s1, v118
	v_or_b32_e32 v119, 3, v116
	v_add_u32_e32 v98, 0, v84
	v_mul_lo_u32 v84, v77, s75
	s_or_b64 s[74:75], s[88:89], vcc
	v_cmp_lt_i32_e32 vcc, s1, v119
	v_or_b32_e32 v120, v86, v107
	s_or_b64 s[96:97], s[88:89], vcc
	v_cmp_lt_i32_e32 vcc, s1, v120
	s_or_b64 s[4:5], s[88:89], vcc
	v_cmp_lt_i32_e32 vcc, s84, v120
	v_or_b32_e32 v122, 2, v120
	s_or_b64 s[26:27], s[88:89], vcc
	v_cmp_lt_i32_e32 vcc, s1, v122
	v_or_b32_e32 v123, 3, v120
	s_or_b64 s[20:21], s[88:89], vcc
	v_cmp_lt_i32_e32 vcc, s1, v123
	v_or_b32_e32 v124, v88, v107
	s_or_b64 s[44:45], s[88:89], vcc
	v_cmp_lt_i32_e32 vcc, s1, v124
	s_or_b64 s[46:47], s[88:89], vcc
	v_cmp_lt_i32_e32 vcc, s84, v124
	v_or_b32_e32 v126, 2, v124
	s_or_b64 s[48:49], s[88:89], vcc
	v_cmp_lt_i32_e32 vcc, s1, v126
	v_or_b32_e32 v127, 3, v124
	s_or_b64 s[50:51], s[88:89], vcc
	v_cmp_lt_i32_e32 vcc, s1, v127
	v_or_b32_e32 v128, v89, v107
	s_or_b64 s[52:53], s[88:89], vcc
	v_cmp_lt_i32_e32 vcc, s1, v128
	s_or_b64 s[54:55], s[88:89], vcc
	v_cmp_lt_i32_e32 vcc, s84, v128
	v_or_b32_e32 v130, 2, v128
	s_or_b64 s[56:57], s[88:89], vcc
	v_cmp_lt_i32_e32 vcc, s1, v130
	v_or_b32_e32 v131, 3, v128
	s_or_b64 s[58:59], s[88:89], vcc
	v_cmp_lt_i32_e32 vcc, s1, v131
	v_or_b32_e32 v132, v93, v107
	s_or_b64 s[42:43], s[88:89], vcc
	v_cmp_lt_i32_e32 vcc, s1, v132
	s_or_b64 s[2:3], s[88:89], vcc
	v_cmp_lt_i32_e32 vcc, s84, v132
	v_or_b32_e32 v134, 2, v132
	s_mul_i32 s92, s8, 0x1b0000
	s_or_b64 s[8:9], s[88:89], vcc
	v_cmp_lt_i32_e32 vcc, s1, v134
	v_or_b32_e32 v135, 3, v132
	s_or_b64 s[12:13], s[88:89], vcc
	v_cmp_lt_i32_e32 vcc, s1, v135
	v_or_b32_e32 v136, v95, v107
	s_or_b64 s[14:15], s[88:89], vcc
	v_cmp_lt_i32_e32 vcc, s1, v136
	s_or_b64 s[16:17], s[88:89], vcc
	v_cmp_lt_i32_e32 vcc, s84, v136
	v_or_b32_e32 v138, 2, v136
	s_or_b64 s[76:77], s[88:89], vcc
	v_cmp_lt_i32_e32 vcc, s1, v138
	v_or_b32_e32 v139, 3, v136
	s_or_b64 s[78:79], s[88:89], vcc
	v_cmp_lt_i32_e32 vcc, s1, v139
	v_or_b32_e32 v140, v97, v107
	s_or_b64 s[80:81], s[88:89], vcc
	v_cmp_lt_i32_e32 vcc, s1, v140
	s_or_b64 s[82:83], s[88:89], vcc
	v_cmp_lt_i32_e32 vcc, s84, v140
	v_or_b32_e32 v142, 2, v140
	s_or_b64 s[84:85], s[88:89], vcc
	v_cmp_lt_i32_e32 vcc, s1, v142
	v_or_b32_e32 v143, 3, v140
	v_lshlrev_b32_e32 v99, 4, v74
	s_or_b64 s[86:87], s[88:89], vcc
	v_cmp_lt_i32_e32 vcc, s1, v143
	v_and_b32_e32 v92, 63, v74
	v_add_u32_e32 v91, 0, v84
	v_and_b32_e32 v99, 0x70, v99
	s_or_b64 s[88:89], s[88:89], vcc
	s_mul_i32 s91, s0, 0x3600000
	v_lshl_add_u32 v84, v76, 1, v91
	v_add_u32_e32 v91, v91, v99
	v_lshrrev_b32_e32 v99, 3, v92
	s_mul_hi_i32 s90, s0, 0x3600000
	s_add_u32 s0, s91, s92
	v_or_b32_e32 v106, v75, v76
	v_bitop3_b32 v113, v81, v107, v81 bitop3:3
	v_mul_u32_u24_e32 v81, 0x210, v76
	v_or_b32_e32 v76, 8, v99
	s_addc_u32 s1, s90, 0
	v_bitop3_b32 v117, v83, v107, v83 bitop3:3
	v_bitop3_b32 v133, v93, v107, v93 bitop3:3
	v_lshl_add_u32 v83, v77, 5, v98
	v_mul_u32_u24_e32 v93, 0x90, v76
	v_mov_b64_e32 v[76:77], s[0:1]
	v_mad_u64_u32 v[76:77], s[0:1], v99, s95, v[76:77]
	v_lshlrev_b32_e32 v72, 9, v72
	v_mov_b32_e32 v73, v169
; DEV f32x4 mfma32(bf16x8 a, bf16x8 b, f32x4 c) { return __builtin_amdgcn_mfma_f32_16x16x32_bf16(a, b, c, 0, 0, 0); }
; DEV void attn_prompt_group(const Params& p, int l, int item, unsigned char* smem) {
;     ...
;     bf16x8 qf[2];
; #pragma unroll
;     for (int ks = 0; ks < 2; ++ks) qf[ks] = __builtin_bit_cast(bf16x8, *(const u32x4*)(Z + (rowbase + qi) * NIN + AQ + h * 64 + ks * 32 + fq * 8));
;     f32x4 s[9];
; #pragma unroll
;     for (int t = 0; t < 9; ++t) {
;       s[t] = (f32x4){0.f, 0.f, 0.f, 0.f};
; #pragma unroll
;       for (int ks = 0; ks < 2; ++ks) s[t] = mfma32(kf[t][ks], qf[ks], s[t]);
;     }
;     const float slope = exp2f(-(float)(h + 1));
;     const float sink = p.in[I_SINKS][l * 8 + h];
;     float mx = sink;
; #pragma unroll
;     for (int t = 0; t < 9; ++t)
; #pragma unroll
;       for (int j = 0; j < 4; ++j) {
;         const int si = (w + t) * 16 + fq * 4 + j;
;         const bool ok = (si > qi) && (si <= 128 + qi) && (nb > 0 || si >= 128);
;         const float sc = ok ? s[t][j] * 0.125f - slope * (float)(128 + qi - si) : -INFINITY;
;         s[t][j] = sc; mx = fmaxf(mx, sc);
	v_mad_i64_i32 v[76:77], s[0:1], v75, s95, v[76:77]
	v_lshl_add_u64 v[76:77], v[76:77], 0, v[72:73]
	v_and_b32_e32 v73, 7, v74
	v_or_b32_e32 v144, 1, v107
	v_lshl_or_b32 v76, v73, 4, v76
	v_or_b32_e32 v72, s91, v72
	v_mov_b32_e32 v73, s90
	v_mul_u32_u24_e32 v92, 0x90, v99
	v_bitop3_b32 v121, v86, v107, v86 bitop3:3
	v_bitop3_b32 v125, v88, v107, v88 bitop3:3
	v_bitop3_b32 v129, v89, v107, v89 bitop3:3
	v_lshl_add_u32 v79, v79, 5, v98
	v_lshl_add_u32 v80, v80, 5, v98
	v_lshl_add_u32 v82, v82, 5, v98
	v_lshl_add_u32 v85, v85, 5, v98
	v_lshl_add_u32 v86, v87, 5, v98
	v_lshl_add_u32 v87, v90, 5, v98
	v_lshl_add_u32 v88, v94, 5, v98
	v_lshl_add_u32 v89, v96, 5, v98
	v_mul_u32_u24_e32 v78, 0x240, v78
	v_mul_u32_u24_e32 v90, 0x90, v144
	v_lshl_add_u64 v[72:73], s[28:29], 0, v[72:73]
	v_bitop3_b32 v109, v107, v75, v107 bitop3:3
	v_bitop3_b32 v137, v95, v107, v95 bitop3:3
	v_bitop3_b32 v141, v97, v107, v97 bitop3:3
	v_or_b32_e32 v145, 2, v107
	v_or_b32_e32 v146, 3, v107
	v_lshl_add_u64 v[100:101], s[28:29], 0, v[76:77]
	v_lshl_add_u64 v[102:103], v[72:73], 0, v[168:169]
	s_mov_b64 s[90:91], 0
	v_add_u32_e32 v147, v83, v81
	v_add_u32_e32 v148, v79, v81
	v_add_u32_e32 v149, v80, v81
	v_add_u32_e32 v150, v82, v81
	v_add_u32_e32 v151, v85, v81
	v_add_u32_e32 v152, v86, v81
	v_add_u32_e32 v153, v87, v81
	v_add_u32_e32 v154, v88, v81
	v_add_u32_e32 v155, v89, v81
	v_add_u32_e32 v156, v84, v78
	v_add_u32_e32 v157, v84, v90
	v_add_u32_e32 v158, v91, v92
	v_add_u32_e32 v159, v91, v93
	s_mov_b32 s94, 0x42fc0000
	s_mov_b32 s0, s92
	s_mov_b32 s1, 0
	v_mov_b64_e32 v[72:73], s[0:1]
	v_mad_i64_i32 v[72:73], s[0:1], v106, s95, v[72:73]
	v_lshl_add_u64 v[72:73], v[102:103], 0, v[72:73]
	v_add_co_u32_e32 v76, vcc, 0x4700000, v72
	s_nop 1
	v_addc_co_u32_e32 v77, vcc, 0, v73, vcc
	global_load_dwordx4 v[234:237], v[76:77], off offset:3072
	global_load_dwordx4 v[238:241], v[76:77], off offset:3136
	global_load_dword v242, v169, s[18:19]
	s_cmp_lg_u32 s92, 0
	s_cselect_b32 s0, -1, 0x7f
	v_add_u32_e32 v184, 0x80, v106
	v_mov_b32_e32 v185, 0x7f800000
	v_sub_u32_e32 v104, v184, v108
	v_add_u32_e32 v105, -3, v104
	v_add_u32_e32 v177, 3, v108
	v_cmp_gt_u32_e32 vcc, 0x80, v105
	v_cmp_lt_i32_e64 s[2:3], s0, v177
	v_cvt_f32_i32_e32 v179, v105
	s_and_b64 vcc, vcc, s[2:3]
	s_nop 1
	v_cndmask_b32_e32 v111, v185, v179, vcc
	v_add_u32_e32 v105, -2, v104
	v_add_u32_e32 v177, 2, v108
	v_cmp_gt_u32_e32 vcc, 0x80, v105
	v_cmp_lt_i32_e64 s[2:3], s0, v177
	v_cvt_f32_i32_e32 v179, v105
	s_and_b64 vcc, vcc, s[2:3]
	s_nop 1
	v_cndmask_b32_e32 v110, v185, v179, vcc
	v_add_u32_e32 v105, -1, v104
	v_add_u32_e32 v177, 1, v108
	v_cmp_gt_u32_e32 vcc, 0x80, v105
	v_cmp_lt_i32_e64 s[2:3], s0, v177
	v_cvt_f32_i32_e32 v179, v105
	s_and_b64 vcc, vcc, s[2:3]
	s_nop 1
	v_cndmask_b32_e32 v109, v185, v179, vcc
	v_cmp_gt_u32_e32 vcc, 0x80, v104
	v_cmp_lt_i32_e64 s[2:3], s0, v108
	v_cvt_f32_i32_e32 v179, v104
	s_and_b64 vcc, vcc, s[2:3]
	s_nop 1
	v_cndmask_b32_e32 v108, v185, v179, vcc
	v_sub_u32_e32 v104, v184, v112
	v_add_u32_e32 v105, -3, v104
	v_add_u32_e32 v177, 3, v112
	v_cmp_gt_u32_e32 vcc, 0x80, v105
	v_cmp_lt_i32_e64 s[2:3], s0, v177
	v_cvt_f32_i32_e32 v179, v105
	s_and_b64 vcc, vcc, s[2:3]
	s_nop 1
	v_cndmask_b32_e32 v115, v185, v179, vcc
	v_add_u32_e32 v105, -2, v104
	v_add_u32_e32 v177, 2, v112
	v_cmp_gt_u32_e32 vcc, 0x80, v105
	v_cmp_lt_i32_e64 s[2:3], s0, v177
	v_cvt_f32_i32_e32 v179, v105
	s_and_b64 vcc, vcc, s[2:3]
	s_nop 1
	v_cndmask_b32_e32 v114, v185, v179, vcc
	v_add_u32_e32 v105, -1, v104
	v_add_u32_e32 v177, 1, v112
	v_cmp_gt_u32_e32 vcc, 0x80, v105
	v_cmp_lt_i32_e64 s[2:3], s0, v177
	v_cvt_f32_i32_e32 v179, v105
	s_and_b64 vcc, vcc, s[2:3]
	s_nop 1
	v_cndmask_b32_e32 v113, v185, v179, vcc
	v_cmp_gt_u32_e32 vcc, 0x80, v104
	v_cmp_lt_i32_e64 s[2:3], s0, v112
	v_cvt_f32_i32_e32 v179, v104
	s_and_b64 vcc, vcc, s[2:3]
	s_nop 1
	v_cndmask_b32_e32 v112, v185, v179, vcc
	v_sub_u32_e32 v104, v184, v116
	v_add_u32_e32 v105, -3, v104
	v_add_u32_e32 v177, 3, v116
	v_cmp_gt_u32_e32 vcc, 0x80, v105
	v_cmp_lt_i32_e64 s[2:3], s0, v177
	v_cvt_f32_i32_e32 v179, v105
	s_and_b64 vcc, vcc, s[2:3]
	s_nop 1
	v_cndmask_b32_e32 v119, v185, v179, vcc
	v_add_u32_e32 v105, -2, v104
	v_add_u32_e32 v177, 2, v116
	v_cmp_gt_u32_e32 vcc, 0x80, v105
	v_cmp_lt_i32_e64 s[2:3], s0, v177
	v_cvt_f32_i32_e32 v179, v105
	s_and_b64 vcc, vcc, s[2:3]
	s_nop 1
	v_cndmask_b32_e32 v118, v185, v179, vcc
	v_add_u32_e32 v105, -1, v104
	v_add_u32_e32 v177, 1, v116
	v_cmp_gt_u32_e32 vcc, 0x80, v105
	v_cmp_lt_i32_e64 s[2:3], s0, v177
	v_cvt_f32_i32_e32 v179, v105
	s_and_b64 vcc, vcc, s[2:3]
	s_nop 1
	v_cndmask_b32_e32 v117, v185, v179, vcc
	v_cmp_gt_u32_e32 vcc, 0x80, v104
	v_cmp_lt_i32_e64 s[2:3], s0, v116
	v_cvt_f32_i32_e32 v179, v104
	s_and_b64 vcc, vcc, s[2:3]
	s_nop 1
	v_cndmask_b32_e32 v116, v185, v179, vcc
	v_sub_u32_e32 v104, v184, v120
	v_add_u32_e32 v105, -3, v104
	v_add_u32_e32 v177, 3, v120
	v_cmp_gt_u32_e32 vcc, 0x80, v105
	v_cmp_lt_i32_e64 s[2:3], s0, v177
	v_cvt_f32_i32_e32 v179, v105
	s_and_b64 vcc, vcc, s[2:3]
	s_nop 1
	v_cndmask_b32_e32 v123, v185, v179, vcc
	v_add_u32_e32 v105, -2, v104
	v_add_u32_e32 v177, 2, v120
	v_cmp_gt_u32_e32 vcc, 0x80, v105
	v_cmp_lt_i32_e64 s[2:3], s0, v177
; DEV void attn_prompt_group(const Params& p, int l, int item, unsigned char* smem) {
;     ...
;   __syncthreads();
;     ...
;     for (int t = 0; t < 9; ++t)
; #pragma unroll
;       for (int j = 0; j < 4; ++j) {
;         const int si = (w + t) * 16 + fq * 4 + j;
;         const bool ok = (si > qi) && (si <= 128 + qi) && (nb > 0 || si >= 128);
;         const float sc = ok ? s[t][j] * 0.125f - slope * (float)(128 + qi - si) : -INFINITY;
;         s[t][j] = sc; mx = fmaxf(mx, sc);
;       }
	v_cvt_f32_i32_e32 v179, v105
	s_and_b64 vcc, vcc, s[2:3]
	s_nop 1
	v_cndmask_b32_e32 v122, v185, v179, vcc
	v_add_u32_e32 v105, -1, v104
	v_add_u32_e32 v177, 1, v120
	v_cmp_gt_u32_e32 vcc, 0x80, v105
	v_cmp_lt_i32_e64 s[2:3], s0, v177
	v_cvt_f32_i32_e32 v179, v105
	s_and_b64 vcc, vcc, s[2:3]
	s_nop 1
	v_cndmask_b32_e32 v121, v185, v179, vcc
	v_cmp_gt_u32_e32 vcc, 0x80, v104
	v_cmp_lt_i32_e64 s[2:3], s0, v120
	v_cvt_f32_i32_e32 v179, v104
	s_and_b64 vcc, vcc, s[2:3]
	s_nop 1
	v_cndmask_b32_e32 v120, v185, v179, vcc
	v_sub_u32_e32 v104, v184, v124
	v_add_u32_e32 v105, -3, v104
	v_add_u32_e32 v177, 3, v124
	v_cmp_gt_u32_e32 vcc, 0x80, v105
	v_cmp_lt_i32_e64 s[2:3], s0, v177
	v_cvt_f32_i32_e32 v179, v105
	s_and_b64 vcc, vcc, s[2:3]
	s_nop 1
	v_cndmask_b32_e32 v127, v185, v179, vcc
	v_add_u32_e32 v105, -2, v104
	v_add_u32_e32 v177, 2, v124
	v_cmp_gt_u32_e32 vcc, 0x80, v105
	v_cmp_lt_i32_e64 s[2:3], s0, v177
	v_cvt_f32_i32_e32 v179, v105
	s_and_b64 vcc, vcc, s[2:3]
	s_nop 1
	v_cndmask_b32_e32 v126, v185, v179, vcc
	v_add_u32_e32 v105, -1, v104
	v_add_u32_e32 v177, 1, v124
	v_cmp_gt_u32_e32 vcc, 0x80, v105
	v_cmp_lt_i32_e64 s[2:3], s0, v177
	v_cvt_f32_i32_e32 v179, v105
	s_and_b64 vcc, vcc, s[2:3]
	s_nop 1
	v_cndmask_b32_e32 v125, v185, v179, vcc
	v_cmp_gt_u32_e32 vcc, 0x80, v104
	v_cmp_lt_i32_e64 s[2:3], s0, v124
	v_cvt_f32_i32_e32 v179, v104
	s_and_b64 vcc, vcc, s[2:3]
	s_nop 1
	v_cndmask_b32_e32 v124, v185, v179, vcc
	v_sub_u32_e32 v104, v184, v128
	v_add_u32_e32 v105, -3, v104
	v_add_u32_e32 v177, 3, v128
	v_cmp_gt_u32_e32 vcc, 0x80, v105
	v_cmp_lt_i32_e64 s[2:3], s0, v177
	v_cvt_f32_i32_e32 v179, v105
	s_and_b64 vcc, vcc, s[2:3]
	s_nop 1
	v_cndmask_b32_e32 v131, v185, v179, vcc
	v_add_u32_e32 v105, -2, v104
	v_add_u32_e32 v177, 2, v128
	v_cmp_gt_u32_e32 vcc, 0x80, v105
	v_cmp_lt_i32_e64 s[2:3], s0, v177
	v_cvt_f32_i32_e32 v179, v105
	s_and_b64 vcc, vcc, s[2:3]
	s_nop 1
	v_cndmask_b32_e32 v130, v185, v179, vcc
	v_add_u32_e32 v105, -1, v104
	v_add_u32_e32 v177, 1, v128
	v_cmp_gt_u32_e32 vcc, 0x80, v105
	v_cmp_lt_i32_e64 s[2:3], s0, v177
	v_cvt_f32_i32_e32 v179, v105
	s_and_b64 vcc, vcc, s[2:3]
	s_nop 1
	v_cndmask_b32_e32 v129, v185, v179, vcc
	v_cmp_gt_u32_e32 vcc, 0x80, v104
	v_cmp_lt_i32_e64 s[2:3], s0, v128
	v_cvt_f32_i32_e32 v179, v104
	s_and_b64 vcc, vcc, s[2:3]
	s_nop 1
	v_cndmask_b32_e32 v128, v185, v179, vcc
	v_sub_u32_e32 v104, v184, v132
	v_add_u32_e32 v105, -3, v104
	v_add_u32_e32 v177, 3, v132
	v_cmp_gt_u32_e32 vcc, 0x80, v105
	v_cmp_lt_i32_e64 s[2:3], s0, v177
	v_cvt_f32_i32_e32 v179, v105
	s_and_b64 vcc, vcc, s[2:3]
	s_nop 1
	v_cndmask_b32_e32 v135, v185, v179, vcc
	v_add_u32_e32 v105, -2, v104
	v_add_u32_e32 v177, 2, v132
	v_cmp_gt_u32_e32 vcc, 0x80, v105
	v_cmp_lt_i32_e64 s[2:3], s0, v177
	v_cvt_f32_i32_e32 v179, v105
	s_and_b64 vcc, vcc, s[2:3]
	s_nop 1
	v_cndmask_b32_e32 v134, v185, v179, vcc
	v_add_u32_e32 v105, -1, v104
	v_add_u32_e32 v177, 1, v132
	v_cmp_gt_u32_e32 vcc, 0x80, v105
	v_cmp_lt_i32_e64 s[2:3], s0, v177
	v_cvt_f32_i32_e32 v179, v105
	s_and_b64 vcc, vcc, s[2:3]
	s_nop 1
	v_cndmask_b32_e32 v133, v185, v179, vcc
	v_cmp_gt_u32_e32 vcc, 0x80, v104
	v_cmp_lt_i32_e64 s[2:3], s0, v132
	v_cvt_f32_i32_e32 v179, v104
	s_and_b64 vcc, vcc, s[2:3]
	s_nop 1
	v_cndmask_b32_e32 v132, v185, v179, vcc
	v_sub_u32_e32 v104, v184, v136
	v_add_u32_e32 v105, -3, v104
	v_add_u32_e32 v177, 3, v136
	v_cmp_gt_u32_e32 vcc, 0x80, v105
	v_cmp_lt_i32_e64 s[2:3], s0, v177
	v_cvt_f32_i32_e32 v179, v105
	s_and_b64 vcc, vcc, s[2:3]
	s_nop 1
	v_cndmask_b32_e32 v139, v185, v179, vcc
	v_add_u32_e32 v105, -2, v104
	v_add_u32_e32 v177, 2, v136
	v_cmp_gt_u32_e32 vcc, 0x80, v105
	v_cmp_lt_i32_e64 s[2:3], s0, v177
	v_cvt_f32_i32_e32 v179, v105
	s_and_b64 vcc, vcc, s[2:3]
	s_nop 1
	v_cndmask_b32_e32 v138, v185, v179, vcc
	v_add_u32_e32 v105, -1, v104
	v_add_u32_e32 v177, 1, v136
	v_cmp_gt_u32_e32 vcc, 0x80, v105
	v_cmp_lt_i32_e64 s[2:3], s0, v177
	v_cvt_f32_i32_e32 v179, v105
	s_and_b64 vcc, vcc, s[2:3]
	s_nop 1
	v_cndmask_b32_e32 v137, v185, v179, vcc
	v_cmp_gt_u32_e32 vcc, 0x80, v104
	v_cmp_lt_i32_e64 s[2:3], s0, v136
	v_cvt_f32_i32_e32 v179, v104
	s_and_b64 vcc, vcc, s[2:3]
	s_nop 1
	v_cndmask_b32_e32 v136, v185, v179, vcc
	v_sub_u32_e32 v104, v184, v140
	v_add_u32_e32 v105, -3, v104
	v_add_u32_e32 v177, 3, v140
	v_cmp_gt_u32_e32 vcc, 0x80, v105
	v_cmp_lt_i32_e64 s[2:3], s0, v177
	v_cvt_f32_i32_e32 v179, v105
	s_and_b64 vcc, vcc, s[2:3]
	s_nop 1
	v_cndmask_b32_e32 v143, v185, v179, vcc
	v_add_u32_e32 v105, -2, v104
	v_add_u32_e32 v177, 2, v140
	v_cmp_gt_u32_e32 vcc, 0x80, v105
	v_cmp_lt_i32_e64 s[2:3], s0, v177
	v_cvt_f32_i32_e32 v179, v105
	s_and_b64 vcc, vcc, s[2:3]
	s_nop 1
	v_cndmask_b32_e32 v142, v185, v179, vcc
	v_add_u32_e32 v105, -1, v104
	v_add_u32_e32 v177, 1, v140
	v_cmp_gt_u32_e32 vcc, 0x80, v105
	v_cmp_lt_i32_e64 s[2:3], s0, v177
	v_cvt_f32_i32_e32 v179, v105
	s_and_b64 vcc, vcc, s[2:3]
	s_nop 1
	v_cndmask_b32_e32 v141, v185, v179, vcc
	v_cmp_gt_u32_e32 vcc, 0x80, v104
	v_cmp_lt_i32_e64 s[2:3], s0, v140
	v_cvt_f32_i32_e32 v179, v104
	s_and_b64 vcc, vcc, s[2:3]
	s_nop 1
	v_cndmask_b32_e32 v140, v185, v179, vcc
	s_mov_b32 s36, 0x3e000000
	s_mov_b32 s37, 0x3e000000
	s_waitcnt lgkmcnt(0)
	s_barrier
	s_waitcnt vmcnt(0)

; DEV f32x4 mfma32(bf16x8 a, bf16x8 b, f32x4 c) { return __builtin_amdgcn_mfma_f32_16x16x32_bf16(a, b, c, 0, 0, 0); }
; DEV void attn_prompt_group(const Params& p, int l, int item, unsigned char* smem) {
;     ...
;     for (int t = 0; t < 9; ++t) {
;       s[t] = (f32x4){0.f, 0.f, 0.f, 0.f};
; #pragma unroll
;       for (int ks = 0; ks < 2; ++ks) s[t] = mfma32(kf[t][ks], qf[ks], s[t]);
;     }
;     const float slope = exp2f(-(float)(h + 1));
;     const float sink = p.in[I_SINKS][l * 8 + h];
;     float mx = sink;
; #pragma unroll
;     for (int t = 0; t < 9; ++t)
; #pragma unroll
;       for (int j = 0; j < 4; ++j) {
;         const int si = (w + t) * 16 + fq * 4 + j;
;         const bool ok = (si > qi) && (si <= 128 + qi) && (nb > 0 || si >= 128);
;         const float sc = ok ? s[t][j] * 0.125f - slope * (float)(128 + qi - si) : -INFINITY;
;         s[t][j] = sc; mx = fmaxf(mx, sc);
;       }
;     mx = fmaxf(mx, __shfl_xor(mx, 16)); mx = fmaxf(mx, __shfl_xor(mx, 32));
.Lattn_noq:
	v_cmp_lt_f32_e32 vcc, s94, v104
	s_and_b64 s[0:1], vcc, exec
	s_cselect_b32 s0, 0xffffffc0, 0
	v_cndmask_b32_e32 v105, 0, v203, vcc
	v_sub_f32_e32 v104, v105, v104
	v_exp_f32_e32 v104, v104
	v_mfma_f32_16x16x32_bf16 v[76:79], v[4:7], v[72:75], 0
	v_ldexp_f32 v105, v104, s0
	v_mfma_f32_16x16x32_bf16 v[164:167], v[0:3], v[160:163], v[76:79]
	v_readfirstlane_b32 s38, v105
	v_mfma_f32_16x16x32_bf16 v[76:79], v[12:15], v[72:75], 0
	s_xor_b32 s38, s38, 0x80000000
	s_mov_b32 s39, s38
	v_mfma_f32_16x16x32_bf16 v[180:183], v[8:11], v[160:163], v[76:79]
	v_mfma_f32_16x16x32_bf16 v[76:79], v[20:23], v[72:75], 0
	v_mfma_f32_16x16x32_bf16 v[96:99], v[16:19], v[160:163], v[76:79]
	v_mfma_f32_16x16x32_bf16 v[76:79], v[28:31], v[72:75], 0
	v_mfma_f32_16x16x32_bf16 v[92:95], v[24:27], v[160:163], v[76:79]
	v_mfma_f32_16x16x32_bf16 v[76:79], v[36:39], v[72:75], 0
	v_mfma_f32_16x16x32_bf16 v[88:91], v[32:35], v[160:163], v[76:79]
	v_mfma_f32_16x16x32_bf16 v[76:79], v[44:47], v[72:75], 0
	v_mfma_f32_16x16x32_bf16 v[84:87], v[40:43], v[160:163], v[76:79]
	v_mfma_f32_16x16x32_bf16 v[76:79], v[52:55], v[72:75], 0
	v_mfma_f32_16x16x32_bf16 v[80:83], v[48:51], v[160:163], v[76:79]
	v_mfma_f32_16x16x32_bf16 v[76:79], v[60:63], v[72:75], 0
	v_mfma_f32_16x16x32_bf16 v[72:75], v[68:71], v[72:75], 0
	v_mfma_f32_16x16x32_bf16 v[76:79], v[56:59], v[160:163], v[76:79]
	v_mfma_f32_16x16x32_bf16 v[72:75], v[64:67], v[160:163], v[72:75]
	v_mov_b32_e32 v160, v242
	s_cmp_eq_u32 s90, 0x180
	s_cbranch_scc1 .Lattn_nos
	global_load_dword v242, v169, s[18:19] offset:4
.Lattn_nos:
	v_pk_mul_f32 v[186:187], v[108:109], s[38:39]
	v_pk_mul_f32 v[188:189], v[110:111], s[38:39]
	v_pk_mul_f32 v[190:191], v[112:113], s[38:39]
	v_pk_mul_f32 v[192:193], v[114:115], s[38:39]
	v_fma_f32 v161, v164, v178, v186
	v_fma_f32 v162, v165, v178, v187
	v_fma_f32 v163, v166, v178, v188
	v_fma_f32 v164, v167, v178, v189
	v_fma_f32 v165, v180, v178, v190
	v_fma_f32 v166, v181, v178, v191
	v_fma_f32 v167, v182, v178, v192
	v_fma_f32 v168, v183, v178, v193
	v_pk_mul_f32 v[186:187], v[116:117], s[38:39]
	v_pk_mul_f32 v[188:189], v[118:119], s[38:39]
	v_pk_fma_f32 v[96:97], v[96:97], s[36:37], v[186:187]
	v_pk_fma_f32 v[98:99], v[98:99], s[36:37], v[188:189]
	v_pk_mul_f32 v[190:191], v[120:121], s[38:39]
	v_pk_mul_f32 v[192:193], v[122:123], s[38:39]
	v_pk_fma_f32 v[92:93], v[92:93], s[36:37], v[190:191]
	v_pk_fma_f32 v[94:95], v[94:95], s[36:37], v[192:193]
	v_pk_mul_f32 v[186:187], v[124:125], s[38:39]
	v_pk_mul_f32 v[188:189], v[126:127], s[38:39]
	v_pk_fma_f32 v[88:89], v[88:89], s[36:37], v[186:187]
	v_pk_fma_f32 v[90:91], v[90:91], s[36:37], v[188:189]
	v_pk_mul_f32 v[190:191], v[128:129], s[38:39]
	v_pk_mul_f32 v[192:193], v[130:131], s[38:39]
	v_pk_fma_f32 v[84:85], v[84:85], s[36:37], v[190:191]
	v_pk_fma_f32 v[86:87], v[86:87], s[36:37], v[192:193]
	v_pk_mul_f32 v[186:187], v[132:133], s[38:39]
	v_pk_mul_f32 v[188:189], v[134:135], s[38:39]
	v_pk_fma_f32 v[80:81], v[80:81], s[36:37], v[186:187]
	v_pk_fma_f32 v[82:83], v[82:83], s[36:37], v[188:189]
	v_pk_mul_f32 v[190:191], v[136:137], s[38:39]
	v_pk_mul_f32 v[192:193], v[138:139], s[38:39]
	v_pk_fma_f32 v[76:77], v[76:77], s[36:37], v[190:191]
	v_pk_fma_f32 v[78:79], v[78:79], s[36:37], v[192:193]
	v_pk_mul_f32 v[186:187], v[140:141], s[38:39]
	v_pk_mul_f32 v[188:189], v[142:143], s[38:39]
	v_pk_fma_f32 v[72:73], v[72:73], s[36:37], v[186:187]
	v_pk_fma_f32 v[74:75], v[74:75], s[36:37], v[188:189]
	v_max3_f32 v186, v160, v161, v162
	v_max3_f32 v187, v163, v164, v165
	v_max3_f32 v186, v186, v166, v167
	v_max3_f32 v187, v187, v168, v96
	v_max3_f32 v186, v186, v97, v98
	v_max3_f32 v187, v187, v99, v92
	v_max3_f32 v186, v186, v93, v94
	v_max3_f32 v187, v187, v95, v88
	v_max3_f32 v186, v186, v89, v90
	v_max3_f32 v187, v187, v91, v84
	v_max3_f32 v186, v186, v85, v86
	v_max3_f32 v187, v187, v87, v80
	v_max3_f32 v186, v186, v81, v82
	v_max3_f32 v187, v187, v83, v76
	v_max3_f32 v186, v186, v77, v78
	v_max3_f32 v187, v187, v79, v72
	v_and_b32_e32 v177, 64, v202
	v_xor_b32_e32 v105, 16, v202
	v_add_u32_e32 v179, 64, v177
	v_max3_f32 v186, v186, v73, v74
	v_cmp_lt_i32_e32 vcc, v105, v179
	v_max3_f32 v104, v186, v187, v75
	s_nop 1
	v_cndmask_b32_e32 v105, v202, v105, vcc
	v_lshlrev_b32_e32 v105, 2, v105
	ds_bpermute_b32 v180, v105, v104
	s_waitcnt lgkmcnt(0)
	v_max_f32_e32 v180, v180, v180
	v_max_f32_e32 v104, v104, v180
	v_xor_b32_e32 v180, 32, v202
	v_cmp_lt_i32_e32 vcc, v180, v179
	s_nop 1
	v_cndmask_b32_e32 v179, v202, v180, vcc
	v_lshlrev_b32_e32 v179, 2, v179
	ds_bpermute_b32 v180, v179, v104
	s_waitcnt lgkmcnt(0)
; DEV f32x4 mfma16(bf16x4 a, bf16x4 b, f32x4 c) { return __builtin_amdgcn_mfma_f32_16x16x16bf16_1k(a, b, c, 0, 0, 0); }
; DEV void attn_prompt_group(const Params& p, int l, int item, unsigned char* smem) {
;     ...
;     float sum = 0.f;
; #pragma unroll
;     for (int t = 0; t < 9; ++t)
; #pragma unroll
;       for (int j = 0; j < 4; ++j) { const float e = __expf(s[t][j] - mx); s[t][j] = e; sum += e; }
;     sum += __shfl_xor(sum, 16); sum += __shfl_xor(sum, 32);
;     const float denom = sum + __expf(sink - mx);
;     f32x4 o[4];
; #pragma unroll
;     for (int dt = 0; dt < 4; ++dt) o[dt] = (f32x4){0.f, 0.f, 0.f, 0.f};
; #pragma unroll
;     for (int t = 0; t < 9; ++t) {
;       const bf16x4 pf = pack4(s[t][0], s[t][1], s[t][2], s[t][3]);
; #pragma unroll
;       for (int dt = 0; dt < 4; ++dt) {
;         const bf16x4 vf = *(const bf16x4*)(Vt + (dt * 16 + fr) * 264 + (w + t) * 16 + fq * 4);
;         o[dt] = mfma16(pf, vf, o[dt]);
;       }
;     }
	v_max_f32_e32 v180, v180, v180
	v_max_f32_e32 v104, v104, v180
	v_sub_f32_e32 v161, v161, v104
	v_mul_f32_e32 v161, 0x3fb8aa3b, v161
	v_sub_f32_e32 v162, v162, v104
	v_exp_f32_e32 v161, v161
	v_mul_f32_e32 v162, 0x3fb8aa3b, v162
	v_sub_f32_e32 v163, v163, v104
	v_exp_f32_e32 v162, v162
	v_mul_f32_e32 v163, 0x3fb8aa3b, v163
	v_sub_f32_e32 v164, v164, v104
	v_exp_f32_e32 v163, v163
	v_mul_f32_e32 v164, 0x3fb8aa3b, v164
	v_sub_f32_e32 v165, v165, v104
	v_exp_f32_e32 v164, v164
	v_mul_f32_e32 v165, 0x3fb8aa3b, v165
	v_sub_f32_e32 v166, v166, v104
	v_add_f32_e32 v180, 0, v161
	v_exp_f32_e32 v165, v165
	v_mul_f32_e32 v166, 0x3fb8aa3b, v166
	v_sub_f32_e32 v167, v167, v104
	v_add_f32_e32 v180, v162, v180
	v_exp_f32_e32 v166, v166
	v_mul_f32_e32 v167, 0x3fb8aa3b, v167
	v_sub_f32_e32 v168, v168, v104
	v_add_f32_e32 v180, v163, v180
	v_exp_f32_e32 v167, v167
	v_mul_f32_e32 v168, 0x3fb8aa3b, v168
	v_sub_f32_e32 v96, v96, v104
	v_add_f32_e32 v180, v164, v180
	v_exp_f32_e32 v168, v168
	v_mul_f32_e32 v96, 0x3fb8aa3b, v96
	v_sub_f32_e32 v97, v97, v104
	v_add_f32_e32 v180, v165, v180
	v_exp_f32_e32 v96, v96
	v_mul_f32_e32 v97, 0x3fb8aa3b, v97
	v_sub_f32_e32 v98, v98, v104
	v_add_f32_e32 v180, v166, v180
	v_exp_f32_e32 v97, v97
	v_mul_f32_e32 v98, 0x3fb8aa3b, v98
	v_sub_f32_e32 v99, v99, v104
	v_add_f32_e32 v180, v167, v180
	v_exp_f32_e32 v98, v98
	v_mul_f32_e32 v99, 0x3fb8aa3b, v99
	v_sub_f32_e32 v92, v92, v104
	v_add_f32_e32 v180, v168, v180
	v_exp_f32_e32 v99, v99
	v_mul_f32_e32 v92, 0x3fb8aa3b, v92
	v_sub_f32_e32 v93, v93, v104
	v_add_f32_e32 v180, v96, v180
	v_exp_f32_e32 v92, v92
	v_mul_f32_e32 v93, 0x3fb8aa3b, v93
	v_sub_f32_e32 v94, v94, v104
	v_add_f32_e32 v180, v97, v180
	v_exp_f32_e32 v93, v93
	v_mul_f32_e32 v94, 0x3fb8aa3b, v94
	v_sub_f32_e32 v95, v95, v104
	v_add_f32_e32 v180, v98, v180
	v_exp_f32_e32 v94, v94
	v_mul_f32_e32 v95, 0x3fb8aa3b, v95
	v_sub_f32_e32 v88, v88, v104
	v_add_f32_e32 v180, v99, v180
	v_exp_f32_e32 v95, v95
	v_mul_f32_e32 v88, 0x3fb8aa3b, v88
	v_add_f32_e32 v180, v92, v180
	v_exp_f32_e32 v181, v88
	v_add_f32_e32 v180, v93, v180
	v_add_f32_e32 v180, v94, v180
	v_sub_f32_e32 v89, v89, v104
	v_add_f32_e32 v180, v95, v180
	v_mul_f32_e32 v89, 0x3fb8aa3b, v89
	v_add_f32_e32 v88, v181, v180
	v_exp_f32_e32 v180, v89
	v_sub_f32_e32 v89, v90, v104
	v_mul_f32_e32 v89, 0x3fb8aa3b, v89
	v_exp_f32_e32 v182, v89
	v_sub_f32_e32 v89, v91, v104
	v_sub_f32_e32 v85, v85, v104
	v_mul_f32_e32 v89, 0x3fb8aa3b, v89
	v_sub_f32_e32 v84, v84, v104
	v_mul_f32_e32 v85, 0x3fb8aa3b, v85
	v_exp_f32_e32 v183, v89
	v_mul_f32_e32 v84, 0x3fb8aa3b, v84
	v_exp_f32_e32 v185, v85
	v_sub_f32_e32 v85, v86, v104
	v_exp_f32_e32 v184, v84
	v_mul_f32_e32 v85, 0x3fb8aa3b, v85
	v_add_f32_e32 v88, v180, v88
	v_exp_f32_e32 v186, v85
	v_sub_f32_e32 v85, v87, v104
	v_sub_f32_e32 v81, v81, v104
	v_add_f32_e32 v88, v182, v88
	v_mul_f32_e32 v85, 0x3fb8aa3b, v85
	v_sub_f32_e32 v80, v80, v104
	v_mul_f32_e32 v81, 0x3fb8aa3b, v81
	v_add_f32_e32 v88, v183, v88
	v_exp_f32_e32 v187, v85
	v_mul_f32_e32 v80, 0x3fb8aa3b, v80
	v_exp_f32_e32 v189, v81
	v_sub_f32_e32 v81, v82, v104
	v_add_f32_e32 v84, v184, v88
	v_exp_f32_e32 v188, v80
	v_mul_f32_e32 v81, 0x3fb8aa3b, v81
	v_add_f32_e32 v84, v185, v84
	v_exp_f32_e32 v190, v81
	v_sub_f32_e32 v81, v83, v104
	v_sub_f32_e32 v77, v77, v104
	v_add_f32_e32 v84, v186, v84
	v_mul_f32_e32 v81, 0x3fb8aa3b, v81
	v_sub_f32_e32 v76, v76, v104
	v_mul_f32_e32 v77, 0x3fb8aa3b, v77
	v_add_f32_e32 v84, v187, v84
	v_exp_f32_e32 v191, v81
	v_mul_f32_e32 v76, 0x3fb8aa3b, v76
	v_exp_f32_e32 v193, v77
	v_sub_f32_e32 v77, v78, v104
	v_add_f32_e32 v80, v188, v84
	v_exp_f32_e32 v192, v76
	v_mul_f32_e32 v77, 0x3fb8aa3b, v77
	v_add_f32_e32 v80, v189, v80
	v_exp_f32_e32 v194, v77
	v_sub_f32_e32 v77, v79, v104
	v_sub_f32_e32 v73, v73, v104
	v_add_f32_e32 v80, v190, v80
	v_mul_f32_e32 v77, 0x3fb8aa3b, v77
	v_sub_f32_e32 v72, v72, v104
	v_mul_f32_e32 v73, 0x3fb8aa3b, v73
	v_add_f32_e32 v80, v191, v80
	v_exp_f32_e32 v195, v77
	v_mul_f32_e32 v72, 0x3fb8aa3b, v72
	v_exp_f32_e32 v197, v73
	v_sub_f32_e32 v73, v74, v104
	v_add_f32_e32 v76, v192, v80
	v_exp_f32_e32 v196, v72
	v_mul_f32_e32 v73, 0x3fb8aa3b, v73
	v_add_f32_e32 v76, v193, v76
	v_exp_f32_e32 v198, v73
	v_sub_f32_e32 v73, v75, v104
	v_add_f32_e32 v76, v194, v76
	v_mul_f32_e32 v73, 0x3fb8aa3b, v73
	v_add_f32_e32 v76, v195, v76
	v_exp_f32_e32 v199, v73
	v_add_f32_e32 v72, v196, v76
	v_add_f32_e32 v72, v197, v72
	v_add_f32_e32 v72, v198, v72
	v_add_f32_e32 v72, v199, v72
	ds_bpermute_b32 v73, v105, v72
	v_cvt_pk_bf16_f32 v84, v161, v162
	v_cvt_pk_bf16_f32 v85, v163, v164
	v_sub_f32_e32 v74, v160, v104
	v_mul_f32_e32 v74, 0x3fb8aa3b, v74
	s_waitcnt lgkmcnt(0)
	v_add_f32_e32 v72, v72, v73
	ds_bpermute_b32 v73, v179, v72
	v_cvt_pk_bf16_f32 v88, v165, v166
	v_cvt_pk_bf16_f32 v89, v167, v168
	ds_read_b64 v[90:91], v148
	v_exp_f32_e32 v104, v74
	s_waitcnt lgkmcnt(1)
	v_add_f32_e32 v105, v72, v73
	ds_read_b64 v[72:73], v147
	ds_read_b64 v[76:77], v147 offset:8448
	ds_read_b64 v[80:81], v147 offset:16896
	ds_read_b64 v[86:87], v147 offset:25344
	s_waitcnt lgkmcnt(3)
	v_mfma_f32_16x16x16_bf16 v[72:75], v[84:85], v[72:73], 0
	v_mfma_f32_16x16x16_bf16 v[72:75], v[88:89], v[90:91], v[72:75]
	ds_read_b64 v[90:91], v148 offset:8448
	s_waitcnt lgkmcnt(3)
	v_mfma_f32_16x16x16_bf16 v[76:79], v[84:85], v[76:77], 0
	s_waitcnt lgkmcnt(0)
	v_mfma_f32_16x16x16_bf16 v[76:79], v[88:89], v[90:91], v[76:79]
	ds_read_b64 v[90:91], v148 offset:16896
	v_mfma_f32_16x16x16_bf16 v[80:83], v[84:85], v[80:81], 0
	s_waitcnt lgkmcnt(0)
	v_mfma_f32_16x16x16_bf16 v[80:83], v[88:89], v[90:91], v[80:83]
	ds_read_b64 v[90:91], v148 offset:25344
	v_mfma_f32_16x16x16_bf16 v[84:87], v[84:85], v[86:87], 0
	s_waitcnt lgkmcnt(0)
; DEV f32x4 mfma16(bf16x4 a, bf16x4 b, f32x4 c) { return __builtin_amdgcn_mfma_f32_16x16x16bf16_1k(a, b, c, 0, 0, 0); }
; DEV void attn_prompt_group(const Params& p, int l, int item, unsigned char* smem) {
;     ...
;     for (int t = 0; t < 9; ++t) {
;       const bf16x4 pf = pack4(s[t][0], s[t][1], s[t][2], s[t][3]);
; #pragma unroll
;       for (int dt = 0; dt < 4; ++dt) {
;         const bf16x4 vf = *(const bf16x4*)(Vt + (dt * 16 + fr) * 264 + (w + t) * 16 + fq * 4);
;         o[dt] = mfma16(pf, vf, o[dt]);
;       }
;     }
;     bf16_t* Os = (bf16_t*)(smem + 33792 + w * 2304);
; #pragma unroll
;     for (int j = 0; j < 4; ++j) {
;       const int r = fq * 4 + j;
;       const float inv = 1.0f / __shfl(denom, r);
	v_mfma_f32_16x16x16_bf16 v[84:87], v[88:89], v[90:91], v[84:87]
	ds_read_b64 v[218:219], v149
	ds_read_b64 v[220:221], v149 offset:8448
	ds_read_b64 v[222:223], v149 offset:16896
	ds_read_b64 v[224:225], v149 offset:25344
	v_cvt_pk_bf16_f32 v88, v96, v97
	v_cvt_pk_bf16_f32 v89, v98, v99
	ds_read_b64 v[226:227], v150
	ds_read_b64 v[228:229], v150 offset:8448
	ds_read_b64 v[230:231], v150 offset:16896
	ds_read_b64 v[232:233], v150 offset:25344
	s_waitcnt lgkmcnt(4)
	v_mfma_f32_16x16x16_bf16 v[72:75], v[88:89], v[218:219], v[72:75]
	v_mfma_f32_16x16x16_bf16 v[76:79], v[88:89], v[220:221], v[76:79]
	v_mfma_f32_16x16x16_bf16 v[80:83], v[88:89], v[222:223], v[80:83]
	v_mfma_f32_16x16x16_bf16 v[84:87], v[88:89], v[224:225], v[84:87]
	v_cvt_pk_bf16_f32 v88, v92, v93
	v_cvt_pk_bf16_f32 v89, v94, v95
	ds_read_b64 v[218:219], v151
	ds_read_b64 v[220:221], v151 offset:8448
	ds_read_b64 v[222:223], v151 offset:16896
	ds_read_b64 v[224:225], v151 offset:25344
	s_waitcnt lgkmcnt(4)
	v_mfma_f32_16x16x16_bf16 v[72:75], v[88:89], v[226:227], v[72:75]
	v_mfma_f32_16x16x16_bf16 v[76:79], v[88:89], v[228:229], v[76:79]
	v_mfma_f32_16x16x16_bf16 v[80:83], v[88:89], v[230:231], v[80:83]
	v_mfma_f32_16x16x16_bf16 v[84:87], v[88:89], v[232:233], v[84:87]
	v_cvt_pk_bf16_f32 v88, v181, v180
	v_cvt_pk_bf16_f32 v89, v182, v183
	ds_read_b64 v[226:227], v152
	ds_read_b64 v[228:229], v152 offset:8448
	ds_read_b64 v[230:231], v152 offset:16896
	ds_read_b64 v[232:233], v152 offset:25344
	s_waitcnt lgkmcnt(4)
	v_mfma_f32_16x16x16_bf16 v[72:75], v[88:89], v[218:219], v[72:75]
	v_mfma_f32_16x16x16_bf16 v[76:79], v[88:89], v[220:221], v[76:79]
	v_mfma_f32_16x16x16_bf16 v[80:83], v[88:89], v[222:223], v[80:83]
	v_mfma_f32_16x16x16_bf16 v[84:87], v[88:89], v[224:225], v[84:87]
	v_cvt_pk_bf16_f32 v88, v184, v185
	v_cvt_pk_bf16_f32 v89, v186, v187
	ds_read_b64 v[218:219], v153
	ds_read_b64 v[220:221], v153 offset:8448
	ds_read_b64 v[222:223], v153 offset:16896
	ds_read_b64 v[224:225], v153 offset:25344
	s_waitcnt lgkmcnt(4)
	v_mfma_f32_16x16x16_bf16 v[72:75], v[88:89], v[226:227], v[72:75]
	v_mfma_f32_16x16x16_bf16 v[76:79], v[88:89], v[228:229], v[76:79]
	v_mfma_f32_16x16x16_bf16 v[80:83], v[88:89], v[230:231], v[80:83]
	v_mfma_f32_16x16x16_bf16 v[84:87], v[88:89], v[232:233], v[84:87]
	v_cvt_pk_bf16_f32 v88, v188, v189
	v_cvt_pk_bf16_f32 v89, v190, v191
	ds_read_b64 v[226:227], v154
	ds_read_b64 v[228:229], v154 offset:8448
	ds_read_b64 v[230:231], v154 offset:16896
	ds_read_b64 v[232:233], v154 offset:25344
	s_waitcnt lgkmcnt(4)
	v_mfma_f32_16x16x16_bf16 v[72:75], v[88:89], v[218:219], v[72:75]
	v_mfma_f32_16x16x16_bf16 v[76:79], v[88:89], v[220:221], v[76:79]
	v_mfma_f32_16x16x16_bf16 v[80:83], v[88:89], v[222:223], v[80:83]
	v_mfma_f32_16x16x16_bf16 v[84:87], v[88:89], v[224:225], v[84:87]
	v_cvt_pk_bf16_f32 v88, v192, v193
	v_cvt_pk_bf16_f32 v89, v194, v195
	ds_read_b64 v[218:219], v155
	ds_read_b64 v[220:221], v155 offset:8448
	ds_read_b64 v[222:223], v155 offset:16896
	ds_read_b64 v[224:225], v155 offset:25344
	s_waitcnt lgkmcnt(4)
	v_mfma_f32_16x16x16_bf16 v[72:75], v[88:89], v[226:227], v[72:75]
	v_mfma_f32_16x16x16_bf16 v[76:79], v[88:89], v[228:229], v[76:79]
	v_mfma_f32_16x16x16_bf16 v[80:83], v[88:89], v[230:231], v[80:83]
	v_mfma_f32_16x16x16_bf16 v[84:87], v[88:89], v[232:233], v[84:87]
	v_cvt_pk_bf16_f32 v88, v196, v197
	v_cvt_pk_bf16_f32 v89, v198, v199
	s_nop 0
	s_waitcnt lgkmcnt(0)
	v_mfma_f32_16x16x16_bf16 v[72:75], v[88:89], v[218:219], v[72:75]
	v_mfma_f32_16x16x16_bf16 v[76:79], v[88:89], v[220:221], v[76:79]
	v_mfma_f32_16x16x16_bf16 v[80:83], v[88:89], v[222:223], v[80:83]
	v_mfma_f32_16x16x16_bf16 v[84:87], v[88:89], v[224:225], v[84:87]
	v_or_b32_e32 v89, v177, v107
	v_add_f32_e32 v88, v104, v105
	v_lshlrev_b32_e32 v89, 2, v89
	ds_bpermute_b32 v89, v89, v88
	s_waitcnt lgkmcnt(0)
; DEV bf16_t f2bf(float f) { return (bf16_t)(cvt_pk_bf16(f, 0.f) & 0xffffu); }
; DEV void attn_prompt_group(const Params& p, int l, int item, unsigned char* smem) {
;     ...
;     bf16_t* Os = (bf16_t*)(smem + 33792 + w * 2304);
; #pragma unroll
;     for (int j = 0; j < 4; ++j) {
;       const int r = fq * 4 + j;
;       const float inv = 1.0f / __shfl(denom, r);
; #pragma unroll
;       for (int dt = 0; dt < 4; ++dt) Os[r * 72 + dt * 16 + fr] = f2bf(o[dt][j] * inv);
;     }
;     asm volatile("s_waitcnt lgkmcnt(0)" ::: "memory");
; #pragma unroll
;     for (int i = 0; i < 2; ++i) {
;       const int c = lane + i * 64, r = c >> 3, kc = c & 7;
;       const u32x4 v = *(const u32x4*)(Os + r * 72 + kc * 8);
;       *(u32x4*)(Z + (rowbase + w * 16 + r) * NIN + AQ + h * 64 + kc * 8) = v;
;     }
;     asm volatile("s_waitcnt lgkmcnt(0)" ::: "memory");
;   }
;   __syncthreads();
	v_div_scale_f32 v90, s[0:1], v89, v89, 1.0
	v_rcp_f32_e32 v91, v90
	s_nop 0
	v_fma_f32 v92, -v90, v91, 1.0
	v_fmac_f32_e32 v91, v92, v91
	v_div_scale_f32 v92, vcc, 1.0, v89, 1.0
	v_mul_f32_e32 v93, v92, v91
	v_fma_f32 v94, -v90, v93, v92
	v_fmac_f32_e32 v93, v94, v91
	v_fma_f32 v90, -v90, v93, v92
	v_div_fmas_f32 v90, v90, v91, v93
	v_div_fixup_f32 v89, v90, v89, 1.0
	v_mul_f32_e32 v72, v72, v89
	v_cvt_pk_bf16_f32 v72, v72, s0
	ds_write_b16 v156, v72 offset:33792
	v_mul_f32_e32 v72, v76, v89
	v_cvt_pk_bf16_f32 v72, v72, s0
	ds_write_b16 v156, v72 offset:33824
	v_mul_f32_e32 v72, v80, v89
	v_cvt_pk_bf16_f32 v72, v72, s0
	ds_write_b16 v156, v72 offset:33856
	v_mul_f32_e32 v72, v84, v89
	v_cvt_pk_bf16_f32 v72, v72, s0
	ds_write_b16 v156, v72 offset:33888
	v_or_b32_e32 v72, v177, v144
	v_lshlrev_b32_e32 v72, 2, v72
	ds_bpermute_b32 v72, v72, v88
	s_waitcnt lgkmcnt(0)
	v_div_scale_f32 v76, s[0:1], v72, v72, 1.0
	v_rcp_f32_e32 v80, v76
	s_nop 0
	v_fma_f32 v84, -v76, v80, 1.0
	v_fmac_f32_e32 v80, v84, v80
	v_div_scale_f32 v84, vcc, 1.0, v72, 1.0
	v_mul_f32_e32 v89, v84, v80
	v_fma_f32 v90, -v76, v89, v84
	v_fmac_f32_e32 v89, v90, v80
	v_fma_f32 v76, -v76, v89, v84
	v_div_fmas_f32 v76, v76, v80, v89
	v_div_fixup_f32 v72, v76, v72, 1.0
	v_mul_f32_e32 v73, v73, v72
	v_cvt_pk_bf16_f32 v73, v73, s0
	ds_write_b16 v157, v73 offset:33792
	v_mul_f32_e32 v73, v77, v72
	v_cvt_pk_bf16_f32 v73, v73, s0
	ds_write_b16 v157, v73 offset:33824
	v_mul_f32_e32 v73, v81, v72
	v_mul_f32_e32 v72, v85, v72
	v_cvt_pk_bf16_f32 v72, v72, s0
	ds_write_b16 v157, v72 offset:33888
	v_or_b32_e32 v72, v177, v145
	v_lshlrev_b32_e32 v72, 2, v72
	ds_bpermute_b32 v72, v72, v88
	v_cvt_pk_bf16_f32 v73, v73, s0
	ds_write_b16 v157, v73 offset:33856
	s_waitcnt lgkmcnt(1)
	v_div_scale_f32 v73, s[0:1], v72, v72, 1.0
	v_rcp_f32_e32 v76, v73
	s_nop 0
	v_fma_f32 v77, -v73, v76, 1.0
	v_fmac_f32_e32 v76, v77, v76
	v_div_scale_f32 v77, vcc, 1.0, v72, 1.0
	v_mul_f32_e32 v80, v77, v76
	v_fma_f32 v81, -v73, v80, v77
	v_fmac_f32_e32 v80, v81, v76
	v_fma_f32 v73, -v73, v80, v77
	v_div_fmas_f32 v73, v73, v76, v80
	v_div_fixup_f32 v72, v73, v72, 1.0
	v_mul_f32_e32 v73, v74, v72
	v_cvt_pk_bf16_f32 v73, v73, s0
	ds_write_b16 v157, v73 offset:33936
	v_mul_f32_e32 v73, v78, v72
	v_cvt_pk_bf16_f32 v73, v73, s0
	ds_write_b16 v157, v73 offset:33968
	v_mul_f32_e32 v73, v82, v72
	v_mul_f32_e32 v72, v86, v72
	v_cvt_pk_bf16_f32 v72, v72, s0
	ds_write_b16 v157, v72 offset:34032
	v_or_b32_e32 v72, v177, v146
	v_lshlrev_b32_e32 v72, 2, v72
	ds_bpermute_b32 v72, v72, v88
	v_cvt_pk_bf16_f32 v73, v73, s0
	ds_write_b16 v157, v73 offset:34000
	s_waitcnt lgkmcnt(1)
	v_div_scale_f32 v73, s[0:1], v72, v72, 1.0
	v_rcp_f32_e32 v74, v73
	s_nop 0
	v_fma_f32 v76, -v73, v74, 1.0
	v_fmac_f32_e32 v74, v76, v74
	v_div_scale_f32 v76, vcc, 1.0, v72, 1.0
	v_mul_f32_e32 v77, v76, v74
	v_fma_f32 v78, -v73, v77, v76
	v_fmac_f32_e32 v77, v78, v74
	v_fma_f32 v73, -v73, v77, v76
	v_div_fmas_f32 v73, v73, v74, v77
	v_div_fixup_f32 v72, v73, v72, 1.0
	v_mul_f32_e32 v73, v75, v72
	v_cvt_pk_bf16_f32 v73, v73, s0
	ds_write_b16 v157, v73 offset:34080
	v_mul_f32_e32 v73, v79, v72
	v_cvt_pk_bf16_f32 v73, v73, s0
	ds_write_b16 v157, v73 offset:34112
	v_mul_f32_e32 v73, v83, v72
	v_mul_f32_e32 v72, v87, v72
	v_cvt_pk_bf16_f32 v73, v73, s0
	v_cvt_pk_bf16_f32 v72, v72, s0
	ds_write_b16 v157, v73 offset:34144
	ds_write_b16 v157, v72 offset:34176
	s_waitcnt lgkmcnt(0)
	ds_read_b128 v[72:75], v158 offset:33792
	v_lshl_add_u64 v[76:77], v[100:101], 0, s[90:91]
	s_mov_b32 s0, 0x4700000
	v_add_co_u32_e32 v78, vcc, s0, v76
	s_mov_b32 s0, 0x471b000
	s_nop 0
	v_addc_co_u32_e32 v79, vcc, 0, v77, vcc
	s_waitcnt lgkmcnt(0)
	global_store_dwordx4 v[78:79], v[72:75], off offset:3072
	ds_read_b128 v[72:75], v159 offset:33792
	v_add_co_u32_e32 v76, vcc, s0, v76
	s_add_u32 s90, s90, 0x80
	s_nop 0
	v_addc_co_u32_e32 v77, vcc, 0, v77, vcc
	s_waitcnt lgkmcnt(0)
	global_store_dwordx4 v[76:77], v[72:75], off offset:3072
	s_addc_u32 s91, s91, 0
	s_waitcnt lgkmcnt(0)
	s_add_u32 s18, s18, 4
	s_addc_u32 s19, s19, 0
	s_add_i32 s6, s6, 1
	s_waitcnt vmcnt(2)
	s_cmpk_lg_i32 s90, 0x200
	s_cbranch_scc1 .LBB0_477
	v_readlane_b32 s76, v248, 47
	v_readlane_b32 s77, v248, 48
	v_readlane_b32 s78, v248, 49
	v_readlane_b32 s79, v248, 50
	v_readlane_b32 s80, v248, 51
	v_readlane_b32 s81, v248, 52
	v_readlane_b32 s82, v248, 53
	v_readlane_b32 s83, v248, 54
	v_readlane_b32 s84, v248, 55
	v_readlane_b32 s85, v248, 56
	v_readlane_b32 s86, v248, 57
	v_readlane_b32 s87, v248, 58
	v_readlane_b32 s88, v248, 59
	v_readlane_b32 s89, v248, 60
	v_readlane_b32 s90, v248, 61
	v_readlane_b32 s91, v248, 62
	s_movk_i32 s75, 0x900
	s_barrier
	s_branch .LBB0_428
